# speedup vs baseline: 1.0084x; 1.0059x over previous
; __device__ __forceinline__ float bf_lo(u32 v) { return __uint_as_float(v << 16); }
; __device__ __forceinline__ float bf_hi(u32 v) { return __uint_as_float(v & 0xffff0000u); }
; template <bool FOX>
; __device__ __forceinline__ void attn_pair(const Params& p, int it, char* smem, const int wv) {
;     ...
;     {
;       const int tid3 = opaque_tid(wv);
;       const int e_lane = tid3 & 63, e_fr = e_lane & 15, e_fq = e_lane >> 4, e_qw = q0 + wv * 32;
;       #pragma unroll
;       for (int qt = 0; qt < 2; ++qt) {
;         const float inv = FOX ? 1.0f / st1[qt] : 1.0f;
;         u16* yrow = Yp + (tok0 + e_qw + qt * 16 + e_fr) * ld + e_fq * 4;
;         #pragma unroll
;         for (int dt = 0; dt < 8; ++dt) {
;           uint2 g = *(const uint2*)(yrow + dt * 16);
;           uint2 pk;
;           pk.x = pack2(o[dt][qt][0] * inv * bf_lo(g.x), o[dt][qt][1] * inv * bf_hi(g.x));
;           pk.y = pack2(o[dt][qt][2] * inv * bf_lo(g.y), o[dt][qt][3] * inv * bf_hi(g.y));
;           *(uint2*)(yrow + dt * 16) = pk;
;         }
;       }
.LBB0_332:
	v_mbcnt_lo_u32_b32 v120, -1, 0
	v_mbcnt_hi_u32_b32 v120, -1, v120
	v_and_b32_e32 v120, 16, v120
	v_lshrrev_b32_e32 v121, 1, v120
	v_add_u32_e32 v120, v120, v121
	v_mov_b32_e32 v121, 0
	v_readlane_b32 s0, v255, 38
	s_lshl_b32 s0, s0, 1
	v_readlane_b32 s1, v255, 31
	s_barrier
	v_mbcnt_lo_u32_b32 v44, -1, 0
	v_mbcnt_hi_u32_b32 v44, -1, v44
	v_readlane_b32 s2, v255, 39
	s_add_u32 s0, s1, s0
	v_readlane_b32 s1, v255, 32
	v_and_or_b32 v46, v44, 15, s2
	v_lshrrev_b32_e32 v44, 1, v44
	s_addc_u32 s1, s1, 0
	v_and_b32_e32 v140, 24, v44
	v_lshl_add_u64 v[44:45], s[0:1], 0, v[140:141]
	s_movk_i32 s13, 0x5000
	v_mad_u64_u32 v[44:45], s[0:1], v46, s13, v[44:45]
	v_readlane_b32 s0, v255, 40
	s_mov_b32 s16, 0x50000
	v_add_co_u32_e32 v46, vcc, s16, v44
	v_mad_i32_i24 v45, s0, v152, v45
	global_load_dwordx2 v[48:49], v[44:45], off
	global_load_dwordx2 v[50:51], v[44:45], off offset:32
	global_load_dwordx2 v[72:73], v[44:45], off offset:64
	global_load_dwordx2 v[74:75], v[44:45], off offset:96
	global_load_dwordx2 v[76:77], v[44:45], off offset:128
	global_load_dwordx2 v[78:79], v[44:45], off offset:160
	global_load_dwordx2 v[80:81], v[44:45], off offset:192
	global_load_dwordx2 v[82:83], v[44:45], off offset:224
	v_addc_co_u32_e32 v47, vcc, 0, v45, vcc
	global_load_dwordx2 v[84:85], v[46:47], off
	global_load_dwordx2 v[86:87], v[46:47], off offset:32
	global_load_dwordx2 v[88:89], v[46:47], off offset:64
	global_load_dwordx2 v[90:91], v[46:47], off offset:96
	global_load_dwordx2 v[92:93], v[46:47], off offset:128
	global_load_dwordx2 v[94:95], v[46:47], off offset:160
	global_load_dwordx2 v[96:97], v[46:47], off offset:192
	global_load_dwordx2 v[98:99], v[46:47], off offset:224
	v_readlane_b32 s68, v255, 11
	v_readlane_b32 s92, v255, 35
	v_readlane_b32 s14, v255, 41
	v_readlane_b32 s70, v255, 13
	v_readlane_b32 s71, v255, 14
	v_readlane_b32 s91, v255, 15
	v_readlane_b32 s93, v255, 36
	v_readlane_b32 s95, v255, 37
	v_readlane_b32 s15, v255, 42
	v_readlane_b32 s69, v255, 12
	s_waitcnt vmcnt(15)
	v_lshlrev_b32_e32 v100, 16, v48
	v_and_b32_e32 v101, 0xffff0000, v48
	v_lshlrev_b32_e32 v48, 16, v49
	v_and_b32_e32 v49, 0xffff0000, v49
	s_waitcnt vmcnt(14)
	v_lshlrev_b32_e32 v102, 16, v50
	v_and_b32_e32 v103, 0xffff0000, v50
	v_lshlrev_b32_e32 v50, 16, v51
	v_and_b32_e32 v51, 0xffff0000, v51
	s_waitcnt vmcnt(13)
	v_lshlrev_b32_e32 v104, 16, v72
	v_and_b32_e32 v105, 0xffff0000, v72
	v_lshlrev_b32_e32 v72, 16, v73
	v_and_b32_e32 v73, 0xffff0000, v73
	s_waitcnt vmcnt(12)
	v_lshlrev_b32_e32 v106, 16, v74
	v_and_b32_e32 v107, 0xffff0000, v74
	v_lshlrev_b32_e32 v74, 16, v75
	v_and_b32_e32 v75, 0xffff0000, v75
	s_waitcnt vmcnt(11)
	v_lshlrev_b32_e32 v108, 16, v76
	v_and_b32_e32 v109, 0xffff0000, v76
	v_lshlrev_b32_e32 v76, 16, v77
	v_and_b32_e32 v77, 0xffff0000, v77
	s_waitcnt vmcnt(10)
	v_lshlrev_b32_e32 v110, 16, v78
	v_and_b32_e32 v111, 0xffff0000, v78
	v_lshlrev_b32_e32 v78, 16, v79
	v_and_b32_e32 v79, 0xffff0000, v79
	v_pk_mul_f32 v[40:41], v[40:41], v[100:101]
	v_pk_mul_f32 v[42:43], v[42:43], v[48:49]
	v_pk_mul_f32 v[48:49], v[68:69], v[102:103]
	v_pk_mul_f32 v[50:51], v[70:71], v[50:51]
	v_pk_mul_f32 v[64:65], v[64:65], v[104:105]
	v_pk_mul_f32 v[66:67], v[66:67], v[72:73]
	v_pk_mul_f32 v[60:61], v[60:61], v[106:107]
	v_pk_mul_f32 v[62:63], v[62:63], v[74:75]
	v_pk_mul_f32 v[56:57], v[56:57], v[108:109]
	v_pk_mul_f32 v[58:59], v[58:59], v[76:77]
	v_pk_mul_f32 v[52:53], v[52:53], v[110:111]
	v_pk_mul_f32 v[54:55], v[54:55], v[78:79]
	v_cvt_pk_bf16_f32 v40, v40, v41
	v_cvt_pk_bf16_f32 v41, v42, v43
	s_waitcnt vmcnt(9)
	v_lshlrev_b32_e32 v112, 16, v80
	v_and_b32_e32 v113, 0xffff0000, v80
	v_cvt_pk_bf16_f32 v42, v48, v49
	v_cvt_pk_bf16_f32 v43, v50, v51
	v_cvt_pk_bf16_f32 v48, v64, v65
	v_cvt_pk_bf16_f32 v49, v66, v67
	v_cvt_pk_bf16_f32 v50, v60, v61
	v_cvt_pk_bf16_f32 v51, v62, v63
	v_cvt_pk_bf16_f32 v56, v56, v57
	v_cvt_pk_bf16_f32 v57, v58, v59
	v_cvt_pk_bf16_f32 v52, v52, v53
	v_cvt_pk_bf16_f32 v53, v54, v55
	v_mov_b32_e32 v116, v40
	v_mov_b32_e32 v117, v41
	v_mov_b32_e32 v118, v42
	v_mov_b32_e32 v119, v43
	v_lshl_add_u64 v[122:123], v[44:45], 0, v[120:121]
	s_nop 0
	v_permlane16_swap_b32_e32 v116, v118
	v_permlane16_swap_b32_e32 v117, v119
	global_store_dwordx4 v[122:123], v[116:119], off
	s_nop 1
	v_mov_b32_e32 v116, v48
	v_mov_b32_e32 v117, v49
	v_mov_b32_e32 v118, v50
	v_mov_b32_e32 v119, v51
	v_lshl_add_u64 v[122:123], v[44:45], 0, v[120:121]
	s_nop 0
	v_permlane16_swap_b32_e32 v116, v118
	v_permlane16_swap_b32_e32 v117, v119
	global_store_dwordx4 v[122:123], v[116:119], off offset:64
	s_nop 1
	v_mov_b32_e32 v116, v56
	v_mov_b32_e32 v117, v57
	v_mov_b32_e32 v118, v52
	v_mov_b32_e32 v119, v53
	v_lshl_add_u64 v[122:123], v[44:45], 0, v[120:121]
	s_nop 0
	v_permlane16_swap_b32_e32 v116, v118
	v_permlane16_swap_b32_e32 v117, v119
	global_store_dwordx4 v[122:123], v[116:119], off offset:128
	s_nop 1
	v_lshlrev_b32_e32 v40, 16, v81
	v_and_b32_e32 v41, 0xffff0000, v81
	v_pk_mul_f32 v[36:37], v[36:37], v[112:113]
	v_pk_mul_f32 v[38:39], v[38:39], v[40:41]
	v_cvt_pk_bf16_f32 v36, v36, v37
	v_cvt_pk_bf16_f32 v37, v38, v39
	v_mov_b32_e32 v116, v36
	v_mov_b32_e32 v117, v37
	s_waitcnt vmcnt(11)
; __device__ __forceinline__ float bf_lo(u32 v) { return __uint_as_float(v << 16); }
; __device__ __forceinline__ float bf_hi(u32 v) { return __uint_as_float(v & 0xffff0000u); }
; template <bool FOX>
; __device__ __forceinline__ void attn_pair(const Params& p, int it, char* smem, const int wv) {
;     ...
;     {
;       const int tid3 = opaque_tid(wv);
;       const int e_lane = tid3 & 63, e_fr = e_lane & 15, e_fq = e_lane >> 4, e_qw = q0 + wv * 32;
;       #pragma unroll
;       for (int qt = 0; qt < 2; ++qt) {
;         const float inv = FOX ? 1.0f / st1[qt] : 1.0f;
;         u16* yrow = Yp + (tok0 + e_qw + qt * 16 + e_fr) * ld + e_fq * 4;
;         #pragma unroll
;         for (int dt = 0; dt < 8; ++dt) {
;           uint2 g = *(const uint2*)(yrow + dt * 16);
;           uint2 pk;
;           pk.x = pack2(o[dt][qt][0] * inv * bf_lo(g.x), o[dt][qt][1] * inv * bf_hi(g.x));
;           pk.y = pack2(o[dt][qt][2] * inv * bf_lo(g.y), o[dt][qt][3] * inv * bf_hi(g.y));
;           *(uint2*)(yrow + dt * 16) = pk;
;         }
;       }
	v_lshlrev_b32_e32 v36, 16, v82
	v_and_b32_e32 v37, 0xffff0000, v82
	v_pk_mul_f32 v[32:33], v[32:33], v[36:37]
	v_lshlrev_b32_e32 v36, 16, v83
	v_and_b32_e32 v37, 0xffff0000, v83
	v_pk_mul_f32 v[34:35], v[34:35], v[36:37]
	v_cvt_pk_bf16_f32 v32, v32, v33
	v_cvt_pk_bf16_f32 v33, v34, v35
	v_mov_b32_e32 v118, v32
	v_mov_b32_e32 v119, v33
	v_lshl_add_u64 v[122:123], v[44:45], 0, v[120:121]
	s_nop 0
	v_permlane16_swap_b32_e32 v116, v118
	v_permlane16_swap_b32_e32 v117, v119
	global_store_dwordx4 v[122:123], v[116:119], off offset:192
	s_nop 1
	s_waitcnt vmcnt(11)
	v_lshlrev_b32_e32 v32, 16, v84
	v_and_b32_e32 v33, 0xffff0000, v84
	v_pk_mul_f32 v[28:29], v[28:29], v[32:33]
	v_lshlrev_b32_e32 v32, 16, v85
	v_and_b32_e32 v33, 0xffff0000, v85
	v_pk_mul_f32 v[30:31], v[30:31], v[32:33]
	v_cvt_pk_bf16_f32 v28, v28, v29
	v_cvt_pk_bf16_f32 v29, v30, v31
	v_mov_b32_e32 v116, v28
	v_mov_b32_e32 v117, v29
	s_waitcnt vmcnt(10)
	v_lshlrev_b32_e32 v28, 16, v86
	v_and_b32_e32 v29, 0xffff0000, v86
	v_pk_mul_f32 v[24:25], v[24:25], v[28:29]
	v_lshlrev_b32_e32 v28, 16, v87
	v_and_b32_e32 v29, 0xffff0000, v87
	v_pk_mul_f32 v[26:27], v[26:27], v[28:29]
	v_cvt_pk_bf16_f32 v24, v24, v25
	v_cvt_pk_bf16_f32 v25, v26, v27
	v_mov_b32_e32 v118, v24
	v_mov_b32_e32 v119, v25
	v_lshl_add_u64 v[122:123], v[46:47], 0, v[120:121]
	s_nop 0
	v_permlane16_swap_b32_e32 v116, v118
	v_permlane16_swap_b32_e32 v117, v119
	global_store_dwordx4 v[122:123], v[116:119], off
	s_nop 1
	s_waitcnt vmcnt(10)
	v_lshlrev_b32_e32 v24, 16, v88
	v_and_b32_e32 v25, 0xffff0000, v88
	v_pk_mul_f32 v[20:21], v[20:21], v[24:25]
	v_lshlrev_b32_e32 v24, 16, v89
	v_and_b32_e32 v25, 0xffff0000, v89
	v_pk_mul_f32 v[22:23], v[22:23], v[24:25]
	v_cvt_pk_bf16_f32 v20, v20, v21
	v_cvt_pk_bf16_f32 v21, v22, v23
	v_mov_b32_e32 v116, v20
	v_mov_b32_e32 v117, v21
	s_waitcnt vmcnt(9)
	v_lshlrev_b32_e32 v20, 16, v90
	v_and_b32_e32 v21, 0xffff0000, v90
	v_pk_mul_f32 v[16:17], v[16:17], v[20:21]
	v_lshlrev_b32_e32 v20, 16, v91
	v_and_b32_e32 v21, 0xffff0000, v91
	v_pk_mul_f32 v[18:19], v[18:19], v[20:21]
	v_cvt_pk_bf16_f32 v16, v16, v17
	v_cvt_pk_bf16_f32 v17, v18, v19
	v_mov_b32_e32 v118, v16
	v_mov_b32_e32 v119, v17
	v_lshl_add_u64 v[122:123], v[46:47], 0, v[120:121]
	s_nop 0
	v_permlane16_swap_b32_e32 v116, v118
	v_permlane16_swap_b32_e32 v117, v119
	global_store_dwordx4 v[122:123], v[116:119], off offset:64
	s_nop 1
	s_waitcnt vmcnt(9)
	v_lshlrev_b32_e32 v16, 16, v92
	v_and_b32_e32 v17, 0xffff0000, v92
	v_pk_mul_f32 v[12:13], v[12:13], v[16:17]
	v_lshlrev_b32_e32 v16, 16, v93
	v_and_b32_e32 v17, 0xffff0000, v93
	v_pk_mul_f32 v[14:15], v[14:15], v[16:17]
	v_cvt_pk_bf16_f32 v12, v12, v13
	v_cvt_pk_bf16_f32 v13, v14, v15
	v_mov_b32_e32 v116, v12
	v_mov_b32_e32 v117, v13
	s_waitcnt vmcnt(8)
	v_lshlrev_b32_e32 v12, 16, v94
	v_and_b32_e32 v13, 0xffff0000, v94
	v_pk_mul_f32 v[8:9], v[8:9], v[12:13]
	v_lshlrev_b32_e32 v12, 16, v95
	v_and_b32_e32 v13, 0xffff0000, v95
	v_pk_mul_f32 v[10:11], v[10:11], v[12:13]
	v_cvt_pk_bf16_f32 v8, v8, v9
	v_cvt_pk_bf16_f32 v9, v10, v11
	v_mov_b32_e32 v118, v8
	v_mov_b32_e32 v119, v9
	v_lshl_add_u64 v[122:123], v[46:47], 0, v[120:121]
	s_nop 0
	v_permlane16_swap_b32_e32 v116, v118
	v_permlane16_swap_b32_e32 v117, v119
	global_store_dwordx4 v[122:123], v[116:119], off offset:128
	s_nop 1
	s_waitcnt vmcnt(8)
	v_lshlrev_b32_e32 v8, 16, v96
	v_and_b32_e32 v9, 0xffff0000, v96
	v_pk_mul_f32 v[4:5], v[4:5], v[8:9]
	v_lshlrev_b32_e32 v8, 16, v97
	v_and_b32_e32 v9, 0xffff0000, v97
	v_pk_mul_f32 v[6:7], v[6:7], v[8:9]
	v_cvt_pk_bf16_f32 v4, v4, v5
	v_cvt_pk_bf16_f32 v5, v6, v7
	v_mov_b32_e32 v116, v4
	v_mov_b32_e32 v117, v5
	s_waitcnt vmcnt(7)
	v_lshlrev_b32_e32 v4, 16, v98
	v_and_b32_e32 v5, 0xffff0000, v98
	v_pk_mul_f32 v[0:1], v[0:1], v[4:5]
	v_lshlrev_b32_e32 v4, 16, v99
	v_and_b32_e32 v5, 0xffff0000, v99
	v_pk_mul_f32 v[2:3], v[2:3], v[4:5]
	v_cvt_pk_bf16_f32 v0, v0, v1
	v_cvt_pk_bf16_f32 v1, v2, v3
	v_mov_b32_e32 v118, v0
	v_mov_b32_e32 v119, v1
	v_lshl_add_u64 v[122:123], v[46:47], 0, v[120:121]
	s_nop 0
	v_permlane16_swap_b32_e32 v116, v118
	v_permlane16_swap_b32_e32 v117, v119
	global_store_dwordx4 v[122:123], v[116:119], off offset:192
	s_nop 1

; __device__ __forceinline__ void gemm_tile(const TileDesc& td, char* shm_c, const int wv) {
;     ...
;   } else if (mode == EPI_NORM) {
;     float* red = (float*)(shm_c + 131072);
;     const int e_wr = e_wid >> 2, e_fq = e_lane >> 4;
;     float ssq[2][2][2];
;     #pragma unroll
;     for (int ai = 0; ai < 2; ++ai)
;     #pragma unroll
;     for (int bj = 0; bj < 2; ++bj)
;     #pragma unroll
;     for (int n = 0; n < 2; ++n) {
;       float t = 0.f;
;       #pragma unroll
;       for (int m = 0; m < 4; ++m) { const f32x4 v = acc[ai][bj][m][n]; t += v[0] * v[0] + v[1] * v[1] + v[2] * v[2] + v[3] * v[3]; }
;       t += sx(t, 16, e_lane); t += sx(t, 32, e_lane);
;       ssq[ai][bj][n] = t;
;       if (e_fq == 0) red[(e_wr * 2 + ai) * 256 + bj * 128 + n * 16 + br_l] = t;
;     }
.LBB0_550:
	s_mov_b64 s[48:49], -1
	s_mov_b64 s[46:47], 0
	s_cmp_lt_i32 s84, 4
	s_mov_b64 s[4:5], 0
	s_cbranch_scc1 .LBB0_578
	s_cmp_gt_i32 s84, 4
	s_cbranch_scc0 .LBB0_575
	s_cmp_gt_i32 s84, 6
	s_mov_b64 s[4:5], -1
	s_cbranch_scc0 .LBB0_570
	v_mul_f32_e32 v131, v125, v125
	v_mul_f32_e32 v132, v117, v117
	v_fmac_f32_e32 v131, v124, v124
	v_fmac_f32_e32 v132, v116, v116
	v_fmac_f32_e32 v131, v126, v126
	v_fmac_f32_e32 v132, v118, v118
	v_fmac_f32_e32 v131, v127, v127
	v_fmac_f32_e32 v132, v119, v119
	v_add_f32_e32 v131, v131, v132
	v_mul_f32_e32 v132, v109, v109
	v_fmac_f32_e32 v132, v108, v108
	v_fmac_f32_e32 v132, v110, v110
	v_fmac_f32_e32 v132, v111, v111
	v_add_f32_e32 v131, v131, v132
	v_mul_f32_e32 v132, v101, v101
	v_fmac_f32_e32 v132, v100, v100
	v_and_b32_e32 v129, 63, v128
	v_fmac_f32_e32 v132, v102, v102
	v_lshlrev_b32_e32 v130, 2, v129
	v_fmac_f32_e32 v132, v103, v103
	v_xor_b32_e32 v128, 64, v130
	v_add_f32_e32 v132, v131, v132
	ds_bpermute_b32 v137, v128, v132
	v_xor_b32_e32 v131, 0x80, v130
	v_cmp_gt_u32_e32 vcc, 16, v129
	v_lshl_add_u32 v130, v164, 2, s63
	s_waitcnt lgkmcnt(0)
	v_add_f32_e32 v132, v132, v137
	ds_bpermute_b32 v137, v131, v132
	s_waitcnt lgkmcnt(0)
	v_add_f32_e32 v129, v132, v137
	s_and_saveexec_b64 s[4:5], vcc
	ds_write_b32 v130, v129
	s_or_b64 exec, exec, s[4:5]
	v_mul_f32_e32 v132, v121, v121
	v_mul_f32_e32 v137, v113, v113
	v_fmac_f32_e32 v132, v120, v120
	v_fmac_f32_e32 v137, v112, v112
	v_fmac_f32_e32 v132, v122, v122
	v_fmac_f32_e32 v137, v114, v114
	v_fmac_f32_e32 v132, v123, v123
	v_fmac_f32_e32 v137, v115, v115
	v_add_f32_e32 v132, v132, v137
	v_mul_f32_e32 v137, v105, v105
	v_fmac_f32_e32 v137, v104, v104
	v_fmac_f32_e32 v137, v106, v106
	v_fmac_f32_e32 v137, v107, v107
	v_add_f32_e32 v132, v132, v137
	v_mul_f32_e32 v137, v97, v97
	v_fmac_f32_e32 v137, v96, v96
	v_fmac_f32_e32 v137, v98, v98
	v_fmac_f32_e32 v137, v99, v99
	v_add_f32_e32 v132, v132, v137
	ds_bpermute_b32 v137, v128, v132
	s_waitcnt lgkmcnt(0)
	v_add_f32_e32 v132, v132, v137
	ds_bpermute_b32 v137, v131, v132
	s_waitcnt lgkmcnt(0)
	v_add_f32_e32 v142, v132, v137
	s_and_saveexec_b64 s[4:5], vcc
	ds_write_b32 v130, v142 offset:64
	s_or_b64 exec, exec, s[4:5]
	v_mul_f32_e32 v132, v93, v93
	v_mul_f32_e32 v137, v85, v85
	v_fmac_f32_e32 v132, v92, v92
	v_fmac_f32_e32 v137, v84, v84
	v_fmac_f32_e32 v132, v94, v94
	v_fmac_f32_e32 v137, v86, v86
	v_fmac_f32_e32 v132, v95, v95
	v_fmac_f32_e32 v137, v87, v87
	v_add_f32_e32 v132, v132, v137
	v_mul_f32_e32 v137, v77, v77
	v_fmac_f32_e32 v137, v76, v76
	v_fmac_f32_e32 v137, v78, v78
	v_fmac_f32_e32 v137, v79, v79
	v_add_f32_e32 v132, v132, v137
	v_mul_f32_e32 v137, v69, v69
	v_fmac_f32_e32 v137, v68, v68
	v_fmac_f32_e32 v137, v70, v70
	v_fmac_f32_e32 v137, v71, v71
	v_add_f32_e32 v132, v132, v137
	ds_bpermute_b32 v137, v128, v132
	s_waitcnt lgkmcnt(0)
	v_add_f32_e32 v132, v132, v137
	ds_bpermute_b32 v137, v131, v132
	s_waitcnt lgkmcnt(0)
	v_add_f32_e32 v140, v132, v137
	s_and_saveexec_b64 s[4:5], vcc
	ds_write_b32 v130, v140 offset:512
	s_or_b64 exec, exec, s[4:5]
	v_mul_f32_e32 v132, v89, v89
	v_mul_f32_e32 v137, v81, v81
	v_fmac_f32_e32 v132, v88, v88
	v_fmac_f32_e32 v137, v80, v80
	v_fmac_f32_e32 v132, v90, v90
	v_fmac_f32_e32 v137, v82, v82
	v_fmac_f32_e32 v132, v91, v91
	v_fmac_f32_e32 v137, v83, v83
	v_add_f32_e32 v132, v132, v137
	v_mul_f32_e32 v137, v73, v73
	v_fmac_f32_e32 v137, v72, v72
	v_fmac_f32_e32 v137, v74, v74
	v_fmac_f32_e32 v137, v75, v75
	v_add_f32_e32 v132, v132, v137
	v_mul_f32_e32 v137, v65, v65
	v_fmac_f32_e32 v137, v64, v64
	v_fmac_f32_e32 v137, v66, v66
	v_fmac_f32_e32 v137, v67, v67
	v_add_f32_e32 v132, v132, v137
	ds_bpermute_b32 v137, v128, v132
	s_waitcnt lgkmcnt(0)
	v_add_f32_e32 v132, v132, v137
	ds_bpermute_b32 v137, v131, v132
	s_waitcnt lgkmcnt(0)
	v_add_f32_e32 v157, v132, v137
	s_and_saveexec_b64 s[4:5], vcc
	ds_write_b32 v130, v157 offset:576
	s_or_b64 exec, exec, s[4:5]
	v_mul_f32_e32 v132, v61, v61
	v_mul_f32_e32 v137, v53, v53
	v_fmac_f32_e32 v132, v60, v60
	v_fmac_f32_e32 v137, v52, v52
	v_fmac_f32_e32 v132, v62, v62
	v_fmac_f32_e32 v137, v54, v54
	v_fmac_f32_e32 v132, v63, v63
	v_fmac_f32_e32 v137, v55, v55
	v_add_f32_e32 v132, v132, v137
	v_mul_f32_e32 v137, v45, v45
	v_fmac_f32_e32 v137, v44, v44
	v_fmac_f32_e32 v137, v46, v46
	v_fmac_f32_e32 v137, v47, v47
	v_add_f32_e32 v132, v132, v137
	v_mul_f32_e32 v137, v37, v37
	v_fmac_f32_e32 v137, v36, v36
	v_fmac_f32_e32 v137, v38, v38
	v_fmac_f32_e32 v137, v39, v39
	v_add_f32_e32 v132, v132, v137
	ds_bpermute_b32 v137, v128, v132
	s_waitcnt lgkmcnt(0)
	v_add_f32_e32 v132, v132, v137
	ds_bpermute_b32 v137, v131, v132
	s_waitcnt lgkmcnt(0)
	v_add_f32_e32 v155, v132, v137
	s_and_saveexec_b64 s[4:5], vcc
	ds_write_b32 v130, v155 offset:1024
	s_or_b64 exec, exec, s[4:5]
	v_mul_f32_e32 v132, v57, v57
	v_mul_f32_e32 v137, v49, v49
	v_fmac_f32_e32 v132, v56, v56
	v_fmac_f32_e32 v137, v48, v48
	v_fmac_f32_e32 v132, v58, v58
	v_fmac_f32_e32 v137, v50, v50
	v_fmac_f32_e32 v132, v59, v59
	v_fmac_f32_e32 v137, v51, v51
	v_add_f32_e32 v132, v132, v137
	v_mul_f32_e32 v137, v41, v41
	v_fmac_f32_e32 v137, v40, v40
	v_fmac_f32_e32 v137, v42, v42
	v_fmac_f32_e32 v137, v43, v43
	v_add_f32_e32 v132, v132, v137
	v_mul_f32_e32 v137, v33, v33
	v_fmac_f32_e32 v137, v32, v32
	v_fmac_f32_e32 v137, v34, v34
	v_fmac_f32_e32 v137, v35, v35
	v_add_f32_e32 v132, v132, v137
	ds_bpermute_b32 v137, v128, v132
	s_waitcnt lgkmcnt(0)
	v_add_f32_e32 v132, v132, v137
	ds_bpermute_b32 v137, v131, v132
	s_waitcnt lgkmcnt(0)
; __device__ __forceinline__ void gemm_tile(const TileDesc& td, char* shm_c, const int wv) {
;     ...
;   } else if (mode == EPI_NORM) {
;     float* red = (float*)(shm_c + 131072);
;     const int e_wr = e_wid >> 2, e_fq = e_lane >> 4;
;     float ssq[2][2][2];
;     #pragma unroll
;     for (int ai = 0; ai < 2; ++ai)
;     #pragma unroll
;     for (int bj = 0; bj < 2; ++bj)
;     #pragma unroll
;     for (int n = 0; n < 2; ++n) {
;       float t = 0.f;
;       #pragma unroll
;       for (int m = 0; m < 4; ++m) { const f32x4 v = acc[ai][bj][m][n]; t += v[0] * v[0] + v[1] * v[1] + v[2] * v[2] + v[3] * v[3]; }
;       t += sx(t, 16, e_lane); t += sx(t, 32, e_lane);
;       ssq[ai][bj][n] = t;
;       if (e_fq == 0) red[(e_wr * 2 + ai) * 256 + bj * 128 + n * 16 + br_l] = t;
;     }
;     __syncthreads();
;     #pragma unroll
;     for (int ai = 0; ai < 2; ++ai)
;     #pragma unroll
;     for (int bj = 0; bj < 2; ++bj)
;     #pragma unroll
;     for (int n = 0; n < 2; ++n) {
;       const float tot = ssq[ai][bj][n] + red[((1 - e_wr) * 2 + ai) * 256 + bj * 128 + n * 16 + br_l];
;       const float rstd = 1.0f / sqrtf(tot * (1.0f / 128.f) + EPS);
;       #pragma unroll
;       for (int m = 0; m < 4; ++m) {
;         const float4 g = *(const float4*)(td.aux + m * 16 + ar_l);
;         f32x4 v = acc[ai][bj][m][n];
;         long o = (long)(td.bcol + bj * 128 + n * 16 + br_l) * td.ldo + (td.brow + ai * 128 + m * 16 + ar_l);
;         uint2 pk; pk.x = pack2(v[0] * rstd * g.x, v[1] * rstd * g.y); pk.y = pack2(v[2] * rstd * g.z, v[3] * rstd * g.w);
;         *(uint2*)(td.outb + o) = pk;
;       }
	v_add_f32_e32 v154, v132, v137
	s_and_saveexec_b64 s[4:5], vcc
	ds_write_b32 v130, v154 offset:1088
	s_or_b64 exec, exec, s[4:5]
	v_mul_f32_e32 v132, v29, v29
	v_mul_f32_e32 v137, v21, v21
	v_fmac_f32_e32 v132, v28, v28
	v_fmac_f32_e32 v137, v20, v20
	v_fmac_f32_e32 v132, v30, v30
	v_fmac_f32_e32 v137, v22, v22
	v_fmac_f32_e32 v132, v31, v31
	v_fmac_f32_e32 v137, v23, v23
	v_add_f32_e32 v132, v132, v137
	v_mul_f32_e32 v137, v13, v13
	v_fmac_f32_e32 v137, v12, v12
	v_fmac_f32_e32 v137, v14, v14
	v_fmac_f32_e32 v137, v15, v15
	v_add_f32_e32 v132, v132, v137
	v_mul_f32_e32 v137, v5, v5
	v_fmac_f32_e32 v137, v4, v4
	v_fmac_f32_e32 v137, v6, v6
	v_fmac_f32_e32 v137, v7, v7
	v_add_f32_e32 v132, v132, v137
	ds_bpermute_b32 v137, v128, v132
	s_waitcnt lgkmcnt(0)
	v_add_f32_e32 v132, v132, v137
	ds_bpermute_b32 v137, v131, v132
	s_waitcnt lgkmcnt(0)
	v_add_f32_e32 v153, v132, v137
	s_and_saveexec_b64 s[4:5], vcc
	ds_write_b32 v130, v153 offset:1536
	s_or_b64 exec, exec, s[4:5]
	v_mul_f32_e32 v132, v25, v25
	v_mul_f32_e32 v137, v17, v17
	v_fmac_f32_e32 v132, v24, v24
	v_fmac_f32_e32 v137, v16, v16
	v_fmac_f32_e32 v132, v26, v26
	v_fmac_f32_e32 v137, v18, v18
	v_fmac_f32_e32 v132, v27, v27
	v_fmac_f32_e32 v137, v19, v19
	v_add_f32_e32 v132, v132, v137
	v_mul_f32_e32 v137, v9, v9
	v_fmac_f32_e32 v137, v8, v8
	v_fmac_f32_e32 v137, v10, v10
	v_fmac_f32_e32 v137, v11, v11
	v_add_f32_e32 v132, v132, v137
	v_mul_f32_e32 v137, v1, v1
	v_fmac_f32_e32 v137, v0, v0
	v_fmac_f32_e32 v137, v2, v2
	v_fmac_f32_e32 v137, v3, v3
	v_add_f32_e32 v132, v132, v137
	ds_bpermute_b32 v128, v128, v132
	s_waitcnt lgkmcnt(0)
	v_add_f32_e32 v128, v132, v128
	ds_bpermute_b32 v131, v131, v128
	s_waitcnt lgkmcnt(0)
	v_add_f32_e32 v152, v128, v131
	s_and_saveexec_b64 s[4:5], vcc
	ds_write_b32 v130, v152 offset:1600
	s_or_b64 exec, exec, s[4:5]
	v_lshlrev_b32_e32 v156, 2, v164
	v_add_u32_e32 v128, s64, v156
	v_add_u32_e32 v141, 0x800, v128
	s_waitcnt vmcnt(0) lgkmcnt(0)
	s_barrier
	ds_read2_b32 v[138:139], v141 offset1:16
	v_or_b32_e32 v158, s50, v164
	s_waitcnt lgkmcnt(0)
	v_add_f32_e32 v128, v129, v138
	v_fmamk_f32 v128, v128, 0x3c000000, v160
	v_cmp_gt_f32_e32 vcc, s81, v128
	v_mul_f32_e32 v129, 0x4f800000, v128
	s_nop 0
	v_cndmask_b32_e32 v128, v128, v129, vcc
	v_sqrt_f32_e32 v129, v128
	s_nop 0
	v_add_u32_e32 v130, -1, v129
	v_fma_f32 v131, -v130, v129, v128
	v_cmp_ge_f32_e64 s[4:5], 0, v131
	v_add_u32_e32 v131, 1, v129
	s_nop 0
	v_cndmask_b32_e64 v130, v129, v130, s[4:5]
	v_fma_f32 v129, -v131, v129, v128
	v_cmp_lt_f32_e64 s[4:5], 0, v129
	s_nop 1
	v_cndmask_b32_e64 v129, v130, v131, s[4:5]
	v_mul_f32_e32 v130, 0x37800000, v129
	v_cndmask_b32_e32 v129, v129, v130, vcc
	v_cmp_class_f32_e32 vcc, v128, v161
	s_nop 1
	v_cndmask_b32_e32 v128, v129, v128, vcc
	v_div_scale_f32 v129, s[2:3], v128, v128, 1.0
	v_rcp_f32_e32 v130, v129
	s_ashr_i32 s2, s50, 31
	s_mul_i32 s2, s34, s2
	v_fma_f32 v131, -v129, v130, 1.0
	v_fmac_f32_e32 v130, v131, v130
	v_div_scale_f32 v131, vcc, 1.0, v128, 1.0
	v_mul_f32_e32 v132, v131, v130
	v_fma_f32 v137, -v129, v132, v131
	v_fmac_f32_e32 v132, v137, v130
	v_lshlrev_b32_e32 v137, 2, v136
	v_mbcnt_lo_u32_b32 v176, -1, 0
	v_mbcnt_hi_u32_b32 v176, -1, v176
	v_and_b32_e32 v176, 16, v176
	v_lshrrev_b32_e32 v177, 1, v176
	v_add_u32_e32 v176, v176, v177
	v_mov_b32_e32 v177, 0
	global_load_dwordx4 v[236:239], v137, s[40:41]
	global_load_dwordx4 v[240:243], v137, s[40:41] offset:64
	global_load_dwordx4 v[244:247], v137, s[40:41] offset:128
	global_load_dwordx4 v[248:251], v137, s[40:41] offset:192
	v_fma_f32 v129, -v129, v132, v131
	v_div_fmas_f32 v129, v129, v130, v132
	v_div_fixup_f32 v132, v129, v128, 1.0
	v_pk_mul_f32 v[148:149], v[124:125], v[132:133] op_sel_hi:[1,0]
	v_mul_lo_u32 v130, s35, v158
	v_mad_u64_u32 v[128:129], s[4:5], s34, v158, 0
	v_add3_u32 v129, v129, s2, v130
	v_add_u32_e32 v130, s14, v136
	v_ashrrev_i32_e32 v131, 31, v130
	v_lshl_add_u64 v[128:129], v[128:129], 1, s[36:37]
	v_pk_mul_f32 v[166:167], v[116:117], v[132:133] op_sel_hi:[1,0]
	v_add_u32_e32 v150, 16, v130
	v_ashrrev_i32_e32 v151, 31, v150
	v_pk_mul_f32 v[168:169], v[108:109], v[132:133] op_sel_hi:[1,0]
	v_pk_mul_f32 v[170:171], v[100:101], v[132:133] op_sel_hi:[1,0]
	s_waitcnt vmcnt(0)
	v_pk_mul_f32 v[144:145], v[236:237], v[148:149]
	s_nop 0
	v_cvt_pk_bf16_f32 v148, v144, v145
	v_pk_mul_f32 v[144:145], v[126:127], v[132:133] op_sel_hi:[1,0]
	s_nop 0
	v_pk_mul_f32 v[144:145], v[238:239], v[144:145]
	s_nop 0
	v_cvt_pk_bf16_f32 v149, v144, v145
	v_lshlrev_b64 v[144:145], 1, v[130:131]
	v_lshl_add_u64 v[146:147], v[128:129], 0, v[144:145]
	v_mov_b32_e32 v172, v148
	v_mov_b32_e32 v173, v149
	v_lshl_add_u64 v[178:179], v[146:147], 0, v[176:177]
	v_add_f32_e32 v131, v142, v139
	v_fmamk_f32 v131, v131, 0x3c000000, v160
	v_cmp_gt_f32_e32 vcc, s81, v131
	v_pk_mul_f32 v[146:147], v[166:167], v[240:241]
	s_nop 0
	v_cvt_pk_bf16_f32 v166, v146, v147
	v_pk_mul_f32 v[146:147], v[118:119], v[132:133] op_sel_hi:[1,0]
	s_nop 0
	v_pk_mul_f32 v[146:147], v[146:147], v[242:243]
	s_nop 0
	v_cvt_pk_bf16_f32 v167, v146, v147
	v_lshlrev_b64 v[146:147], 1, v[150:151]
	v_lshl_add_u64 v[148:149], v[128:129], 0, v[146:147]
	v_mov_b32_e32 v174, v166
	v_mov_b32_e32 v175, v167
	s_nop 1
	v_permlane16_swap_b32_e32 v172, v174
	v_permlane16_swap_b32_e32 v173, v175
	global_store_dwordx4 v[178:179], v[172:175], off
	s_nop 1
	v_add_u32_e32 v166, 32, v130
	v_ashrrev_i32_e32 v167, 31, v166
	v_pk_mul_f32 v[148:149], v[168:169], v[244:245]
	s_nop 0
	v_cvt_pk_bf16_f32 v168, v148, v149
	v_pk_mul_f32 v[148:149], v[110:111], v[132:133] op_sel_hi:[1,0]
	s_nop 0
	v_pk_mul_f32 v[148:149], v[148:149], v[246:247]
	s_nop 0
; __device__ __forceinline__ void gemm_tile(const TileDesc& td, char* shm_c, const int wv) {
;     ...
;     #pragma unroll
;     for (int ai = 0; ai < 2; ++ai)
;     #pragma unroll
;     for (int bj = 0; bj < 2; ++bj)
;     #pragma unroll
;     for (int n = 0; n < 2; ++n) {
;       const float tot = ssq[ai][bj][n] + red[((1 - e_wr) * 2 + ai) * 256 + bj * 128 + n * 16 + br_l];
;       const float rstd = 1.0f / sqrtf(tot * (1.0f / 128.f) + EPS);
;       #pragma unroll
;       for (int m = 0; m < 4; ++m) {
;         const float4 g = *(const float4*)(td.aux + m * 16 + ar_l);
;         f32x4 v = acc[ai][bj][m][n];
;         long o = (long)(td.bcol + bj * 128 + n * 16 + br_l) * td.ldo + (td.brow + ai * 128 + m * 16 + ar_l);
;         uint2 pk; pk.x = pack2(v[0] * rstd * g.x, v[1] * rstd * g.y); pk.y = pack2(v[2] * rstd * g.z, v[3] * rstd * g.w);
;         *(uint2*)(td.outb + o) = pk;
;       }
	v_cvt_pk_bf16_f32 v169, v148, v149
	v_lshlrev_b64 v[148:149], 1, v[166:167]
	v_lshl_add_u64 v[150:151], v[128:129], 0, v[148:149]
	v_mov_b32_e32 v172, v168
	v_mov_b32_e32 v173, v169
	v_lshl_add_u64 v[178:179], v[150:151], 0, v[176:177]
	v_add_u32_e32 v150, 48, v130
	v_ashrrev_i32_e32 v151, 31, v150
	v_lshlrev_b64 v[150:151], 1, v[150:151]
	v_pk_mul_f32 v[166:167], v[170:171], v[248:249]
	v_pk_mul_f32 v[170:171], v[102:103], v[132:133] op_sel_hi:[1,0]
	v_cvt_pk_bf16_f32 v166, v166, v167
	v_pk_mul_f32 v[168:169], v[170:171], v[250:251]
	v_mul_f32_e32 v132, 0x4f800000, v131
	v_cvt_pk_bf16_f32 v167, v168, v169
	v_lshl_add_u64 v[168:169], v[128:129], 0, v[150:151]
	v_mov_b32_e32 v174, v166
	v_mov_b32_e32 v175, v167
	s_nop 1
	v_permlane16_swap_b32_e32 v172, v174
	v_permlane16_swap_b32_e32 v173, v175
	global_store_dwordx4 v[178:179], v[172:175], off
	s_nop 1
	v_cndmask_b32_e32 v131, v131, v132, vcc
	v_sqrt_f32_e32 v132, v131
	s_nop 0
	v_add_u32_e32 v138, -1, v132
	v_fma_f32 v139, -v138, v132, v131
	v_cmp_ge_f32_e64 s[4:5], 0, v139
	v_add_u32_e32 v139, 1, v132
	s_nop 0
	v_cndmask_b32_e64 v138, v132, v138, s[4:5]
	v_fma_f32 v132, -v139, v132, v131
	v_cmp_lt_f32_e64 s[4:5], 0, v132
	s_nop 1
	v_cndmask_b32_e64 v132, v138, v139, s[4:5]
	v_mul_f32_e32 v138, 0x37800000, v132
	v_cndmask_b32_e32 v132, v132, v138, vcc
	v_cmp_class_f32_e32 vcc, v131, v161
	s_nop 1
	v_cndmask_b32_e32 v131, v132, v131, vcc
	v_div_scale_f32 v132, s[4:5], v131, v131, 1.0
	v_rcp_f32_e32 v138, v132
	s_nop 0
	v_fma_f32 v139, -v132, v138, 1.0
	v_fmac_f32_e32 v138, v139, v138
	v_div_scale_f32 v139, vcc, 1.0, v131, 1.0
	v_mul_f32_e32 v142, v139, v138
	v_fma_f32 v143, -v132, v142, v139
	v_fmac_f32_e32 v142, v143, v138
	v_fma_f32 v132, -v132, v142, v139
	v_div_fmas_f32 v132, v132, v138, v142
	v_div_fixup_f32 v132, v132, v131, 1.0
	v_or_b32_e32 v131, 16, v158
	v_mul_lo_u32 v142, s35, v131
	v_mad_u64_u32 v[138:139], s[4:5], s34, v131, 0
	v_add3_u32 v139, v139, s2, v142
	v_pk_mul_f32 v[142:143], v[120:121], v[132:133] op_sel_hi:[1,0]
	v_lshl_add_u64 v[138:139], v[138:139], 1, s[36:37]
	v_pk_mul_f32 v[142:143], v[236:237], v[142:143]
	v_pk_mul_f32 v[166:167], v[122:123], v[132:133] op_sel_hi:[1,0]
	v_cvt_pk_bf16_f32 v142, v142, v143
	v_pk_mul_f32 v[166:167], v[238:239], v[166:167]
	s_nop 0
	v_cvt_pk_bf16_f32 v143, v166, v167
	v_lshl_add_u64 v[166:167], v[138:139], 0, v[144:145]
	v_mov_b32_e32 v172, v142
	v_mov_b32_e32 v173, v143
	v_lshl_add_u64 v[178:179], v[166:167], 0, v[176:177]
	v_pk_mul_f32 v[142:143], v[112:113], v[132:133] op_sel_hi:[1,0]
	v_pk_mul_f32 v[142:143], v[142:143], v[240:241]
	v_pk_mul_f32 v[166:167], v[114:115], v[132:133] op_sel_hi:[1,0]
	v_cvt_pk_bf16_f32 v142, v142, v143
	v_pk_mul_f32 v[166:167], v[166:167], v[242:243]
	s_nop 0
	v_cvt_pk_bf16_f32 v143, v166, v167
	v_lshl_add_u64 v[166:167], v[138:139], 0, v[146:147]
	v_mov_b32_e32 v174, v142
	v_mov_b32_e32 v175, v143
	s_nop 1
	v_permlane16_swap_b32_e32 v172, v174
	v_permlane16_swap_b32_e32 v173, v175
	global_store_dwordx4 v[178:179], v[172:175], off
	s_nop 1
	v_pk_mul_f32 v[142:143], v[104:105], v[132:133] op_sel_hi:[1,0]
	v_pk_mul_f32 v[142:143], v[142:143], v[244:245]
	v_pk_mul_f32 v[166:167], v[106:107], v[132:133] op_sel_hi:[1,0]
	v_cvt_pk_bf16_f32 v142, v142, v143
	v_pk_mul_f32 v[166:167], v[166:167], v[246:247]
	s_nop 0
	v_cvt_pk_bf16_f32 v143, v166, v167
	v_lshl_add_u64 v[166:167], v[138:139], 0, v[148:149]
	v_mov_b32_e32 v172, v142
	v_mov_b32_e32 v173, v143
	v_lshl_add_u64 v[178:179], v[166:167], 0, v[176:177]
	v_pk_mul_f32 v[142:143], v[96:97], v[132:133] op_sel_hi:[1,0]
	v_pk_mul_f32 v[142:143], v[142:143], v[248:249]
	v_pk_mul_f32 v[166:167], v[98:99], v[132:133] op_sel_hi:[1,0]
	v_cvt_pk_bf16_f32 v142, v142, v143
	v_pk_mul_f32 v[166:167], v[166:167], v[250:251]
	s_nop 0
	v_cvt_pk_bf16_f32 v143, v166, v167
	v_lshl_add_u64 v[166:167], v[138:139], 0, v[150:151]
	v_mov_b32_e32 v174, v142
	v_mov_b32_e32 v175, v143
	s_nop 1
	v_permlane16_swap_b32_e32 v172, v174
	v_permlane16_swap_b32_e32 v173, v175
	global_store_dwordx4 v[178:179], v[172:175], off
	s_nop 1
	ds_read2_b32 v[142:143], v141 offset0:128 offset1:144
	s_waitcnt lgkmcnt(0)
	v_add_f32_e32 v131, v140, v142
	v_fmamk_f32 v131, v131, 0x3c000000, v160
	v_cmp_gt_f32_e32 vcc, s81, v131
	v_mul_f32_e32 v132, 0x4f800000, v131
	s_nop 0
	v_cndmask_b32_e32 v131, v131, v132, vcc
	v_sqrt_f32_e32 v132, v131
	s_nop 0
	v_add_u32_e32 v140, -1, v132
	v_fma_f32 v141, -v140, v132, v131
	v_cmp_ge_f32_e64 s[4:5], 0, v141
	v_add_u32_e32 v141, 1, v132
	s_nop 0
	v_cndmask_b32_e64 v140, v132, v140, s[4:5]
	v_fma_f32 v132, -v141, v132, v131
	v_cmp_lt_f32_e64 s[4:5], 0, v132
	s_nop 1
	v_cndmask_b32_e64 v132, v140, v141, s[4:5]
	v_mul_f32_e32 v140, 0x37800000, v132
	v_cndmask_b32_e32 v132, v132, v140, vcc
	v_cmp_class_f32_e32 vcc, v131, v161
	s_nop 1
	v_cndmask_b32_e32 v131, v132, v131, vcc
	v_div_scale_f32 v132, s[4:5], v131, v131, 1.0
	v_rcp_f32_e32 v140, v132
	s_nop 0
	v_fma_f32 v141, -v132, v140, 1.0
	v_fmac_f32_e32 v140, v141, v140
	v_div_scale_f32 v141, vcc, 1.0, v131, 1.0
	v_mul_f32_e32 v142, v141, v140
	v_fma_f32 v159, -v132, v142, v141
	v_fmac_f32_e32 v142, v159, v140
	v_fma_f32 v132, -v132, v142, v141
	v_div_fmas_f32 v132, v132, v140, v142
	v_div_fixup_f32 v132, v132, v131, 1.0
	v_or_b32_e32 v131, 0x80, v158
	v_mul_lo_u32 v142, s35, v131
	v_mad_u64_u32 v[140:141], s[4:5], s34, v131, 0
	v_pk_mul_f32 v[170:171], v[92:93], v[132:133] op_sel_hi:[1,0]
	v_add3_u32 v141, v141, s2, v142
	v_lshl_add_u64 v[140:141], v[140:141], 1, s[36:37]
	v_add_f32_e32 v131, v157, v143
	v_fmamk_f32 v131, v131, 0x3c000000, v160
	v_cmp_gt_f32_e32 vcc, s81, v131
	v_pk_mul_f32 v[166:167], v[236:237], v[170:171]
; __device__ __forceinline__ void gemm_tile(const TileDesc& td, char* shm_c, const int wv) {
;     ...
;     #pragma unroll
;     for (int ai = 0; ai < 2; ++ai)
;     #pragma unroll
;     for (int bj = 0; bj < 2; ++bj)
;     #pragma unroll
;     for (int n = 0; n < 2; ++n) {
;       const float tot = ssq[ai][bj][n] + red[((1 - e_wr) * 2 + ai) * 256 + bj * 128 + n * 16 + br_l];
;       const float rstd = 1.0f / sqrtf(tot * (1.0f / 128.f) + EPS);
;       #pragma unroll
;       for (int m = 0; m < 4; ++m) {
;         const float4 g = *(const float4*)(td.aux + m * 16 + ar_l);
;         f32x4 v = acc[ai][bj][m][n];
;         long o = (long)(td.bcol + bj * 128 + n * 16 + br_l) * td.ldo + (td.brow + ai * 128 + m * 16 + ar_l);
;         uint2 pk; pk.x = pack2(v[0] * rstd * g.x, v[1] * rstd * g.y); pk.y = pack2(v[2] * rstd * g.z, v[3] * rstd * g.w);
;         *(uint2*)(td.outb + o) = pk;
;       }
	v_pk_mul_f32 v[170:171], v[94:95], v[132:133] op_sel_hi:[1,0]
	v_cvt_pk_bf16_f32 v166, v166, v167
	v_pk_mul_f32 v[168:169], v[238:239], v[170:171]
	v_pk_mul_f32 v[170:171], v[84:85], v[132:133] op_sel_hi:[1,0]
	v_cvt_pk_bf16_f32 v167, v168, v169
	v_lshl_add_u64 v[168:169], v[140:141], 0, v[144:145]
	v_mov_b32_e32 v172, v166
	v_mov_b32_e32 v173, v167
	v_lshl_add_u64 v[178:179], v[168:169], 0, v[176:177]
	v_pk_mul_f32 v[166:167], v[170:171], v[240:241]
	v_pk_mul_f32 v[170:171], v[86:87], v[132:133] op_sel_hi:[1,0]
	v_cvt_pk_bf16_f32 v166, v166, v167
	v_pk_mul_f32 v[168:169], v[170:171], v[242:243]
	v_pk_mul_f32 v[170:171], v[76:77], v[132:133] op_sel_hi:[1,0]
	v_cvt_pk_bf16_f32 v167, v168, v169
	v_lshl_add_u64 v[168:169], v[140:141], 0, v[146:147]
	v_mov_b32_e32 v174, v166
	v_mov_b32_e32 v175, v167
	s_nop 1
	v_permlane16_swap_b32_e32 v172, v174
	v_permlane16_swap_b32_e32 v173, v175
	global_store_dwordx4 v[178:179], v[172:175], off
	s_nop 1
	v_pk_mul_f32 v[166:167], v[170:171], v[244:245]
	v_pk_mul_f32 v[170:171], v[78:79], v[132:133] op_sel_hi:[1,0]
	v_cvt_pk_bf16_f32 v166, v166, v167
	v_pk_mul_f32 v[168:169], v[170:171], v[246:247]
	v_pk_mul_f32 v[170:171], v[68:69], v[132:133] op_sel_hi:[1,0]
	v_cvt_pk_bf16_f32 v167, v168, v169
	v_lshl_add_u64 v[168:169], v[140:141], 0, v[148:149]
	v_mov_b32_e32 v172, v166
	v_mov_b32_e32 v173, v167
	v_lshl_add_u64 v[178:179], v[168:169], 0, v[176:177]
	v_pk_mul_f32 v[166:167], v[170:171], v[248:249]
	v_pk_mul_f32 v[170:171], v[70:71], v[132:133] op_sel_hi:[1,0]
	v_cvt_pk_bf16_f32 v166, v166, v167
	v_pk_mul_f32 v[168:169], v[170:171], v[250:251]
	v_mul_f32_e32 v132, 0x4f800000, v131
	v_cvt_pk_bf16_f32 v167, v168, v169
	v_lshl_add_u64 v[168:169], v[140:141], 0, v[150:151]
	v_mov_b32_e32 v174, v166
	v_mov_b32_e32 v175, v167
	s_nop 1
	v_permlane16_swap_b32_e32 v172, v174
	v_permlane16_swap_b32_e32 v173, v175
	global_store_dwordx4 v[178:179], v[172:175], off
	s_nop 1
	v_cndmask_b32_e32 v131, v131, v132, vcc
	v_sqrt_f32_e32 v132, v131
	s_nop 0
	v_add_u32_e32 v142, -1, v132
	v_fma_f32 v143, -v142, v132, v131
	v_cmp_ge_f32_e64 s[4:5], 0, v143
	v_add_u32_e32 v143, 1, v132
	s_nop 0
	v_cndmask_b32_e64 v142, v132, v142, s[4:5]
	v_fma_f32 v132, -v143, v132, v131
	v_cmp_lt_f32_e64 s[4:5], 0, v132
	s_nop 1
	v_cndmask_b32_e64 v132, v142, v143, s[4:5]
	v_mul_f32_e32 v142, 0x37800000, v132
	v_cndmask_b32_e32 v132, v132, v142, vcc
	v_cmp_class_f32_e32 vcc, v131, v161
	s_nop 1
	v_cndmask_b32_e32 v131, v132, v131, vcc
	v_div_scale_f32 v132, s[4:5], v131, v131, 1.0
	v_rcp_f32_e32 v142, v132
	s_nop 0
	v_fma_f32 v143, -v132, v142, 1.0
	v_fmac_f32_e32 v142, v143, v142
	v_div_scale_f32 v143, vcc, 1.0, v131, 1.0
	v_mul_f32_e32 v157, v143, v142
	v_fma_f32 v159, -v132, v157, v143
	v_fmac_f32_e32 v157, v159, v142
	v_fma_f32 v132, -v132, v157, v143
	v_div_fmas_f32 v132, v132, v142, v157
	v_div_fixup_f32 v132, v132, v131, 1.0
	v_or_b32_e32 v131, 0x90, v158
	v_mul_lo_u32 v157, s35, v131
	v_mad_u64_u32 v[142:143], s[4:5], s34, v131, 0
	v_pk_mul_f32 v[158:159], v[88:89], v[132:133] op_sel_hi:[1,0]
	v_add3_u32 v143, v143, s2, v157
	v_lshl_add_u64 v[142:143], v[142:143], 1, s[36:37]
	v_lshl_add_u64 v[144:145], v[142:143], 0, v[144:145]
	v_lshl_add_u64 v[146:147], v[142:143], 0, v[146:147]
	v_add_u32_e32 v131, s65, v156
	v_add_u32_e32 v156, 0x800, v131
	v_pk_mul_f32 v[158:159], v[236:237], v[158:159]
	v_pk_mul_f32 v[166:167], v[90:91], v[132:133] op_sel_hi:[1,0]
	v_cvt_pk_bf16_f32 v158, v158, v159
	v_pk_mul_f32 v[166:167], v[238:239], v[166:167]
	s_nop 0
	v_cvt_pk_bf16_f32 v159, v166, v167
	v_mov_b32_e32 v172, v158
	v_mov_b32_e32 v173, v159
	v_lshl_add_u64 v[178:179], v[144:145], 0, v[176:177]
	v_pk_mul_f32 v[144:145], v[80:81], v[132:133] op_sel_hi:[1,0]
	v_pk_mul_f32 v[158:159], v[82:83], v[132:133] op_sel_hi:[1,0]
	v_pk_mul_f32 v[144:145], v[144:145], v[240:241]
	v_pk_mul_f32 v[158:159], v[158:159], v[242:243]
	v_cvt_pk_bf16_f32 v144, v144, v145
	v_cvt_pk_bf16_f32 v145, v158, v159
	v_mov_b32_e32 v174, v144
	v_mov_b32_e32 v175, v145
	s_nop 1
	v_permlane16_swap_b32_e32 v172, v174
	v_permlane16_swap_b32_e32 v173, v175
	global_store_dwordx4 v[178:179], v[172:175], off
	s_nop 1
	v_pk_mul_f32 v[158:159], v[72:73], v[132:133] op_sel_hi:[1,0]
	v_pk_mul_f32 v[144:145], v[158:159], v[244:245]
	v_pk_mul_f32 v[158:159], v[74:75], v[132:133] op_sel_hi:[1,0]
	v_cvt_pk_bf16_f32 v144, v144, v145
	v_pk_mul_f32 v[146:147], v[158:159], v[246:247]
	s_nop 0
	v_cvt_pk_bf16_f32 v145, v146, v147
	v_lshl_add_u64 v[146:147], v[142:143], 0, v[148:149]
	v_mov_b32_e32 v172, v144
	v_mov_b32_e32 v173, v145
	v_lshl_add_u64 v[178:179], v[146:147], 0, v[176:177]
	v_pk_mul_f32 v[148:149], v[64:65], v[132:133] op_sel_hi:[1,0]
	v_pk_mul_f32 v[144:145], v[148:149], v[248:249]
	v_pk_mul_f32 v[148:149], v[66:67], v[132:133] op_sel_hi:[1,0]
	v_cvt_pk_bf16_f32 v144, v144, v145
	v_pk_mul_f32 v[146:147], v[148:149], v[250:251]
	v_add_u32_e32 v148, 0x80, v130
	v_cvt_pk_bf16_f32 v145, v146, v147
	v_lshl_add_u64 v[146:147], v[142:143], 0, v[150:151]
	ds_read2_b32 v[150:151], v156 offset1:16
	v_mov_b32_e32 v174, v144
	v_mov_b32_e32 v175, v145
	s_nop 1
	v_permlane16_swap_b32_e32 v172, v174
	v_permlane16_swap_b32_e32 v173, v175
	global_store_dwordx4 v[178:179], v[172:175], off
	s_nop 1
	v_ashrrev_i32_e32 v149, 31, v148
	s_waitcnt lgkmcnt(0)
; __device__ __forceinline__ void gemm_tile(const TileDesc& td, char* shm_c, const int wv) {
;     ...
;     #pragma unroll
;     for (int ai = 0; ai < 2; ++ai)
;     #pragma unroll
;     for (int bj = 0; bj < 2; ++bj)
;     #pragma unroll
;     for (int n = 0; n < 2; ++n) {
;       const float tot = ssq[ai][bj][n] + red[((1 - e_wr) * 2 + ai) * 256 + bj * 128 + n * 16 + br_l];
;       const float rstd = 1.0f / sqrtf(tot * (1.0f / 128.f) + EPS);
;       #pragma unroll
;       for (int m = 0; m < 4; ++m) {
;         const float4 g = *(const float4*)(td.aux + m * 16 + ar_l);
;         f32x4 v = acc[ai][bj][m][n];
;         long o = (long)(td.bcol + bj * 128 + n * 16 + br_l) * td.ldo + (td.brow + ai * 128 + m * 16 + ar_l);
;         uint2 pk; pk.x = pack2(v[0] * rstd * g.x, v[1] * rstd * g.y); pk.y = pack2(v[2] * rstd * g.z, v[3] * rstd * g.w);
;         *(uint2*)(td.outb + o) = pk;
;       }
	v_add_f32_e32 v131, v155, v150
	v_fmamk_f32 v131, v131, 0x3c000000, v160
	v_cmp_gt_f32_e32 vcc, s81, v131
	v_mul_f32_e32 v132, 0x4f800000, v131
	s_nop 0
	v_cndmask_b32_e32 v131, v131, v132, vcc
	v_sqrt_f32_e32 v132, v131
	s_nop 0
	v_add_u32_e32 v144, -1, v132
	v_fma_f32 v145, -v144, v132, v131
	v_cmp_ge_f32_e64 s[4:5], 0, v145
	v_add_u32_e32 v145, 1, v132
	s_nop 0
	v_cndmask_b32_e64 v144, v132, v144, s[4:5]
	v_fma_f32 v132, -v145, v132, v131
	v_cmp_lt_f32_e64 s[4:5], 0, v132
	s_nop 1
	v_cndmask_b32_e64 v132, v144, v145, s[4:5]
	v_mul_f32_e32 v144, 0x37800000, v132
	v_cndmask_b32_e32 v132, v132, v144, vcc
	v_cmp_class_f32_e32 vcc, v131, v161
	s_nop 1
	v_cndmask_b32_e32 v131, v132, v131, vcc
	v_div_scale_f32 v132, s[2:3], v131, v131, 1.0
	v_rcp_f32_e32 v144, v132
	s_nop 0
	v_fma_f32 v145, -v132, v144, 1.0
	v_fmac_f32_e32 v144, v145, v144
	v_div_scale_f32 v145, vcc, 1.0, v131, 1.0
	v_mul_f32_e32 v146, v145, v144
	v_fma_f32 v147, -v132, v146, v145
	v_fmac_f32_e32 v146, v147, v144
	v_fma_f32 v132, -v132, v146, v145
	v_div_fmas_f32 v132, v132, v144, v146
	v_div_fixup_f32 v132, v132, v131, 1.0
	v_pk_mul_f32 v[158:159], v[60:61], v[132:133] op_sel_hi:[1,0]
	v_pk_mul_f32 v[166:167], v[52:53], v[132:133] op_sel_hi:[1,0]
	v_pk_mul_f32 v[144:145], v[236:237], v[158:159]
	s_nop 0
	v_cvt_pk_bf16_f32 v158, v144, v145
	v_pk_mul_f32 v[144:145], v[62:63], v[132:133] op_sel_hi:[1,0]
	s_nop 0
	v_pk_mul_f32 v[144:145], v[238:239], v[144:145]
	s_nop 0
	v_cvt_pk_bf16_f32 v159, v144, v145
	v_lshlrev_b64 v[144:145], 1, v[148:149]
	v_lshl_add_u64 v[146:147], v[128:129], 0, v[144:145]
	v_mov_b32_e32 v172, v158
	v_mov_b32_e32 v173, v159
	v_lshl_add_u64 v[178:179], v[146:147], 0, v[176:177]
	v_add_u32_e32 v158, 0x90, v130
	v_ashrrev_i32_e32 v159, 31, v158
	v_pk_mul_f32 v[146:147], v[166:167], v[240:241]
	s_nop 0
	v_cvt_pk_bf16_f32 v166, v146, v147
	v_pk_mul_f32 v[146:147], v[54:55], v[132:133] op_sel_hi:[1,0]
	s_nop 0
	v_pk_mul_f32 v[146:147], v[146:147], v[242:243]
	s_nop 0
	v_cvt_pk_bf16_f32 v167, v146, v147
	v_lshlrev_b64 v[146:147], 1, v[158:159]
	v_lshl_add_u64 v[148:149], v[128:129], 0, v[146:147]
	v_mov_b32_e32 v174, v166
	v_mov_b32_e32 v175, v167
	s_nop 1
	v_permlane16_swap_b32_e32 v172, v174
	v_permlane16_swap_b32_e32 v173, v175
	global_store_dwordx4 v[178:179], v[172:175], off
	s_nop 1
	v_add_u32_e32 v148, 0xa0, v130
	v_pk_mul_f32 v[158:159], v[44:45], v[132:133] op_sel_hi:[1,0]
	v_ashrrev_i32_e32 v149, 31, v148
	v_lshlrev_b64 v[148:149], 1, v[148:149]
	v_add_u32_e32 v130, 0xb0, v130
	v_ashrrev_i32_e32 v131, 31, v130
	v_lshlrev_b64 v[130:131], 1, v[130:131]
	v_pk_mul_f32 v[158:159], v[158:159], v[244:245]
	v_pk_mul_f32 v[166:167], v[46:47], v[132:133] op_sel_hi:[1,0]
	v_cvt_pk_bf16_f32 v158, v158, v159
	v_pk_mul_f32 v[166:167], v[166:167], v[246:247]
	s_nop 0
	v_cvt_pk_bf16_f32 v159, v166, v167
	v_lshl_add_u64 v[166:167], v[128:129], 0, v[148:149]
	v_mov_b32_e32 v172, v158
	v_mov_b32_e32 v173, v159
	v_lshl_add_u64 v[178:179], v[166:167], 0, v[176:177]
	v_pk_mul_f32 v[158:159], v[36:37], v[132:133] op_sel_hi:[1,0]
	v_lshl_add_u64 v[128:129], v[128:129], 0, v[130:131]
	v_pk_mul_f32 v[158:159], v[158:159], v[248:249]
	v_pk_mul_f32 v[166:167], v[38:39], v[132:133] op_sel_hi:[1,0]
	v_cvt_pk_bf16_f32 v158, v158, v159
	v_pk_mul_f32 v[166:167], v[166:167], v[250:251]
	s_nop 0
	v_cvt_pk_bf16_f32 v159, v166, v167
	v_mov_b32_e32 v174, v158
	v_mov_b32_e32 v175, v159
	s_nop 1
	v_permlane16_swap_b32_e32 v172, v174
	v_permlane16_swap_b32_e32 v173, v175
	global_store_dwordx4 v[178:179], v[172:175], off
	s_nop 1
	v_add_f32_e32 v128, v154, v151
	v_fmamk_f32 v128, v128, 0x3c000000, v160
	v_cmp_gt_f32_e32 vcc, s81, v128
	v_mul_f32_e32 v129, 0x4f800000, v128
	s_nop 0
	v_cndmask_b32_e32 v128, v128, v129, vcc
	v_sqrt_f32_e32 v129, v128
	s_nop 0
	v_add_u32_e32 v132, -1, v129
	v_fma_f32 v150, -v132, v129, v128
	v_cmp_ge_f32_e64 s[4:5], 0, v150
	v_add_u32_e32 v150, 1, v129
	s_nop 0
	v_cndmask_b32_e64 v132, v129, v132, s[4:5]
	v_fma_f32 v129, -v150, v129, v128
	v_cmp_lt_f32_e64 s[4:5], 0, v129
	s_nop 1
	v_cndmask_b32_e64 v129, v132, v150, s[4:5]
	v_mul_f32_e32 v132, 0x37800000, v129
	v_cndmask_b32_e32 v129, v129, v132, vcc
	v_cmp_class_f32_e32 vcc, v128, v161
	s_nop 1
	v_cndmask_b32_e32 v128, v129, v128, vcc
	v_div_scale_f32 v129, s[2:3], v128, v128, 1.0
	v_rcp_f32_e32 v132, v129
	s_nop 0
	v_fma_f32 v150, -v129, v132, 1.0
	v_fmac_f32_e32 v132, v150, v132
	v_div_scale_f32 v150, vcc, 1.0, v128, 1.0
	v_mul_f32_e32 v151, v150, v132
	v_fma_f32 v154, -v129, v151, v150
	v_fmac_f32_e32 v151, v154, v132
	v_fma_f32 v129, -v129, v151, v150
	v_div_fmas_f32 v129, v129, v132, v151
	v_div_fixup_f32 v128, v129, v128, 1.0
	v_pk_mul_f32 v[150:151], v[56:57], v[128:129] op_sel_hi:[1,0]
	v_pk_mul_f32 v[154:155], v[58:59], v[128:129] op_sel_hi:[1,0]
	v_pk_mul_f32 v[150:151], v[236:237], v[150:151]
	v_pk_mul_f32 v[154:155], v[238:239], v[154:155]
	v_cvt_pk_bf16_f32 v150, v150, v151
	v_cvt_pk_bf16_f32 v151, v154, v155
	v_lshl_add_u64 v[154:155], v[138:139], 0, v[144:145]
	v_mov_b32_e32 v172, v150
	v_mov_b32_e32 v173, v151
	v_lshl_add_u64 v[178:179], v[154:155], 0, v[176:177]
	v_pk_mul_f32 v[150:151], v[48:49], v[128:129] op_sel_hi:[1,0]
	v_pk_mul_f32 v[154:155], v[50:51], v[128:129] op_sel_hi:[1,0]
	v_pk_mul_f32 v[150:151], v[150:151], v[240:241]
	v_pk_mul_f32 v[154:155], v[154:155], v[242:243]
	v_cvt_pk_bf16_f32 v150, v150, v151
	v_cvt_pk_bf16_f32 v151, v154, v155
	v_lshl_add_u64 v[154:155], v[138:139], 0, v[146:147]
	v_mov_b32_e32 v174, v150
	v_mov_b32_e32 v175, v151
	s_nop 1
	v_permlane16_swap_b32_e32 v172, v174
	v_permlane16_swap_b32_e32 v173, v175
	global_store_dwordx4 v[178:179], v[172:175], off
	s_nop 1
	v_pk_mul_f32 v[150:151], v[40:41], v[128:129] op_sel_hi:[1,0]
	v_pk_mul_f32 v[154:155], v[42:43], v[128:129] op_sel_hi:[1,0]
	v_pk_mul_f32 v[150:151], v[150:151], v[244:245]
	v_pk_mul_f32 v[154:155], v[154:155], v[246:247]
	v_cvt_pk_bf16_f32 v150, v150, v151
	v_cvt_pk_bf16_f32 v151, v154, v155
	v_lshl_add_u64 v[154:155], v[138:139], 0, v[148:149]
	v_mov_b32_e32 v172, v150
	v_mov_b32_e32 v173, v151
	v_lshl_add_u64 v[178:179], v[154:155], 0, v[176:177]
	v_pk_mul_f32 v[150:151], v[32:33], v[128:129] op_sel_hi:[1,0]
	v_pk_mul_f32 v[128:129], v[34:35], v[128:129] op_sel_hi:[1,0]
	v_pk_mul_f32 v[150:151], v[150:151], v[248:249]
	v_pk_mul_f32 v[128:129], v[128:129], v[250:251]
	v_cvt_pk_bf16_f32 v150, v150, v151
	v_cvt_pk_bf16_f32 v151, v128, v129
	v_lshl_add_u64 v[128:129], v[138:139], 0, v[130:131]
	v_mov_b32_e32 v174, v150
	v_mov_b32_e32 v175, v151
	s_nop 1
	v_permlane16_swap_b32_e32 v172, v174
	v_permlane16_swap_b32_e32 v173, v175
	global_store_dwordx4 v[178:179], v[172:175], off
	s_nop 1
	ds_read2_b32 v[128:129], v156 offset0:128 offset1:144
	s_waitcnt lgkmcnt(0)
; __device__ __forceinline__ void gemm_tile(const TileDesc& td, char* shm_c, const int wv) {
;     ...
;     #pragma unroll
;     for (int ai = 0; ai < 2; ++ai)
;     #pragma unroll
;     for (int bj = 0; bj < 2; ++bj)
;     #pragma unroll
;     for (int n = 0; n < 2; ++n) {
;       const float tot = ssq[ai][bj][n] + red[((1 - e_wr) * 2 + ai) * 256 + bj * 128 + n * 16 + br_l];
;       const float rstd = 1.0f / sqrtf(tot * (1.0f / 128.f) + EPS);
;       #pragma unroll
;       for (int m = 0; m < 4; ++m) {
;         const float4 g = *(const float4*)(td.aux + m * 16 + ar_l);
;         f32x4 v = acc[ai][bj][m][n];
;         long o = (long)(td.bcol + bj * 128 + n * 16 + br_l) * td.ldo + (td.brow + ai * 128 + m * 16 + ar_l);
;         uint2 pk; pk.x = pack2(v[0] * rstd * g.x, v[1] * rstd * g.y); pk.y = pack2(v[2] * rstd * g.z, v[3] * rstd * g.w);
;         *(uint2*)(td.outb + o) = pk;
;       }
	v_add_f32_e32 v128, v153, v128
	v_fmamk_f32 v128, v128, 0x3c000000, v160
	v_cmp_gt_f32_e32 vcc, s81, v128
	v_mul_f32_e32 v132, 0x4f800000, v128
	s_nop 0
	v_cndmask_b32_e32 v128, v128, v132, vcc
	v_sqrt_f32_e32 v132, v128
	s_nop 0
	v_add_u32_e32 v138, -1, v132
	v_fma_f32 v139, -v138, v132, v128
	v_cmp_ge_f32_e64 s[4:5], 0, v139
	v_add_u32_e32 v139, 1, v132
	s_nop 0
	v_cndmask_b32_e64 v138, v132, v138, s[4:5]
	v_fma_f32 v132, -v139, v132, v128
	v_cmp_lt_f32_e64 s[4:5], 0, v132
	s_nop 1
	v_cndmask_b32_e64 v132, v138, v139, s[4:5]
	v_mul_f32_e32 v138, 0x37800000, v132
	v_cndmask_b32_e32 v132, v132, v138, vcc
	v_cmp_class_f32_e32 vcc, v128, v161
	s_nop 1
	v_cndmask_b32_e32 v128, v132, v128, vcc
	v_div_scale_f32 v132, s[2:3], v128, v128, 1.0
	v_rcp_f32_e32 v138, v132
	s_nop 0
	v_fma_f32 v139, -v132, v138, 1.0
	v_fmac_f32_e32 v138, v139, v138
	v_div_scale_f32 v139, vcc, 1.0, v128, 1.0
	v_mul_f32_e32 v150, v139, v138
	v_fma_f32 v151, -v132, v150, v139
	v_fmac_f32_e32 v150, v151, v138
	v_fma_f32 v132, -v132, v150, v139
	v_div_fmas_f32 v132, v132, v138, v150
	v_div_fixup_f32 v128, v132, v128, 1.0
	v_pk_mul_f32 v[138:139], v[28:29], v[128:129] op_sel_hi:[1,0]
	v_pk_mul_f32 v[150:151], v[30:31], v[128:129] op_sel_hi:[1,0]
	v_pk_mul_f32 v[138:139], v[236:237], v[138:139]
	v_pk_mul_f32 v[150:151], v[238:239], v[150:151]
	v_cvt_pk_bf16_f32 v138, v138, v139
	v_cvt_pk_bf16_f32 v139, v150, v151
	v_lshl_add_u64 v[150:151], v[140:141], 0, v[144:145]
	v_mov_b32_e32 v172, v138
	v_mov_b32_e32 v173, v139
	v_lshl_add_u64 v[178:179], v[150:151], 0, v[176:177]
	v_pk_mul_f32 v[138:139], v[20:21], v[128:129] op_sel_hi:[1,0]
	v_pk_mul_f32 v[150:151], v[22:23], v[128:129] op_sel_hi:[1,0]
	v_pk_mul_f32 v[138:139], v[138:139], v[240:241]
	v_pk_mul_f32 v[150:151], v[150:151], v[242:243]
	v_cvt_pk_bf16_f32 v138, v138, v139
	v_cvt_pk_bf16_f32 v139, v150, v151
	v_lshl_add_u64 v[150:151], v[140:141], 0, v[146:147]
	v_mov_b32_e32 v174, v138
	v_mov_b32_e32 v175, v139
	s_nop 1
	v_permlane16_swap_b32_e32 v172, v174
	v_permlane16_swap_b32_e32 v173, v175
	global_store_dwordx4 v[178:179], v[172:175], off
	s_nop 1
	v_pk_mul_f32 v[138:139], v[12:13], v[128:129] op_sel_hi:[1,0]
	v_pk_mul_f32 v[150:151], v[14:15], v[128:129] op_sel_hi:[1,0]
	v_pk_mul_f32 v[138:139], v[138:139], v[244:245]
	v_pk_mul_f32 v[150:151], v[150:151], v[246:247]
	v_cvt_pk_bf16_f32 v138, v138, v139
	v_cvt_pk_bf16_f32 v139, v150, v151
	v_lshl_add_u64 v[150:151], v[140:141], 0, v[148:149]
	v_mov_b32_e32 v172, v138
	v_mov_b32_e32 v173, v139
	v_lshl_add_u64 v[178:179], v[150:151], 0, v[176:177]
	v_pk_mul_f32 v[138:139], v[4:5], v[128:129] op_sel_hi:[1,0]
	v_pk_mul_f32 v[150:151], v[6:7], v[128:129] op_sel_hi:[1,0]
	v_add_f32_e32 v128, v152, v129
	v_fmamk_f32 v128, v128, 0x3c000000, v160
	v_cmp_gt_f32_e32 vcc, s81, v128
	v_mul_f32_e32 v129, 0x4f800000, v128
	v_lshl_add_u64 v[140:141], v[140:141], 0, v[130:131]
	v_cndmask_b32_e32 v128, v128, v129, vcc
	v_sqrt_f32_e32 v129, v128
	v_pk_mul_f32 v[138:139], v[138:139], v[248:249]
	v_pk_mul_f32 v[150:151], v[150:151], v[250:251]
	v_cvt_pk_bf16_f32 v138, v138, v139
	v_cvt_pk_bf16_f32 v139, v150, v151
	v_add_u32_e32 v132, -1, v129
	v_mov_b32_e32 v174, v138
	v_mov_b32_e32 v175, v139
	s_nop 1
	v_permlane16_swap_b32_e32 v172, v174
	v_permlane16_swap_b32_e32 v173, v175
	global_store_dwordx4 v[178:179], v[172:175], off
	s_nop 1
	v_fma_f32 v138, -v132, v129, v128
	v_cmp_ge_f32_e64 s[4:5], 0, v138
	v_add_u32_e32 v138, 1, v129
	s_nop 0
	v_cndmask_b32_e64 v132, v129, v132, s[4:5]
	v_fma_f32 v129, -v138, v129, v128
	v_cmp_lt_f32_e64 s[4:5], 0, v129
	s_nop 1
	v_cndmask_b32_e64 v129, v132, v138, s[4:5]
	v_mul_f32_e32 v132, 0x37800000, v129
	v_cndmask_b32_e32 v129, v129, v132, vcc
	v_cmp_class_f32_e32 vcc, v128, v161
	s_mov_b64 s[4:5], 0
	s_nop 0
	v_cndmask_b32_e32 v128, v129, v128, vcc
	v_div_scale_f32 v129, s[2:3], v128, v128, 1.0
	v_rcp_f32_e32 v132, v129
	s_nop 0
	v_fma_f32 v138, -v129, v132, 1.0
	v_fmac_f32_e32 v132, v138, v132
	v_div_scale_f32 v138, vcc, 1.0, v128, 1.0
	v_mul_f32_e32 v139, v138, v132
	v_fma_f32 v140, -v129, v139, v138
	v_fmac_f32_e32 v139, v140, v132
	v_fma_f32 v129, -v129, v139, v138
	v_div_fmas_f32 v129, v129, v132, v139
	v_div_fixup_f32 v128, v129, v128, 1.0
	v_pk_mul_f32 v[150:151], v[24:25], v[128:129] op_sel_hi:[1,0]
	v_pk_mul_f32 v[138:139], v[236:237], v[150:151]
	v_pk_mul_f32 v[150:151], v[26:27], v[128:129] op_sel_hi:[1,0]
	v_cvt_pk_bf16_f32 v138, v138, v139
	v_pk_mul_f32 v[140:141], v[238:239], v[150:151]
	s_nop 0
	v_cvt_pk_bf16_f32 v139, v140, v141
	v_lshl_add_u64 v[140:141], v[142:143], 0, v[144:145]
	v_mov_b32_e32 v172, v138
	v_mov_b32_e32 v173, v139
	v_lshl_add_u64 v[178:179], v[140:141], 0, v[176:177]
	v_pk_mul_f32 v[144:145], v[16:17], v[128:129] op_sel_hi:[1,0]
	v_pk_mul_f32 v[138:139], v[144:145], v[240:241]
	v_pk_mul_f32 v[144:145], v[18:19], v[128:129] op_sel_hi:[1,0]
	v_cvt_pk_bf16_f32 v138, v138, v139
	v_pk_mul_f32 v[140:141], v[144:145], v[242:243]
	v_pk_mul_f32 v[144:145], v[8:9], v[128:129] op_sel_hi:[1,0]
	v_cvt_pk_bf16_f32 v139, v140, v141
	v_lshl_add_u64 v[140:141], v[142:143], 0, v[146:147]
	v_mov_b32_e32 v174, v138
	v_mov_b32_e32 v175, v139
	s_nop 1
	v_permlane16_swap_b32_e32 v172, v174
	v_permlane16_swap_b32_e32 v173, v175
	global_store_dwordx4 v[178:179], v[172:175], off
	s_nop 1
	v_pk_mul_f32 v[138:139], v[144:145], v[244:245]
	v_pk_mul_f32 v[144:145], v[10:11], v[128:129] op_sel_hi:[1,0]
	v_cvt_pk_bf16_f32 v138, v138, v139
	v_pk_mul_f32 v[140:141], v[144:145], v[246:247]
	v_pk_mul_f32 v[144:145], v[0:1], v[128:129] op_sel_hi:[1,0]
	v_cvt_pk_bf16_f32 v139, v140, v141
	v_lshl_add_u64 v[140:141], v[142:143], 0, v[148:149]
	v_mov_b32_e32 v172, v138
	v_mov_b32_e32 v173, v139
	v_lshl_add_u64 v[178:179], v[140:141], 0, v[176:177]
	v_pk_mul_f32 v[128:129], v[2:3], v[128:129] op_sel_hi:[1,0]
	v_pk_mul_f32 v[138:139], v[144:145], v[248:249]
	v_pk_mul_f32 v[128:129], v[128:129], v[250:251]
	v_cvt_pk_bf16_f32 v138, v138, v139
	v_cvt_pk_bf16_f32 v139, v128, v129
	v_lshl_add_u64 v[128:129], v[142:143], 0, v[130:131]
	v_mov_b32_e32 v174, v138
	v_mov_b32_e32 v175, v139
	s_nop 1
	v_permlane16_swap_b32_e32 v172, v174
	v_permlane16_swap_b32_e32 v173, v175
	global_store_dwordx4 v[178:179], v[172:175], off
	s_nop 1

; __device__ __forceinline__ float bf_lo(u32 v) { return __uint_as_float(v << 16); }
; __device__ __forceinline__ float bf_hi(u32 v) { return __uint_as_float(v & 0xffff0000u); }
; template <bool FOX>
; __device__ __forceinline__ void attn_pair(const Params& p, int it, char* smem, const int wv) {
;     ...
;     {
;       const int tid3 = opaque_tid(wv);
;       const int e_lane = tid3 & 63, e_fr = e_lane & 15, e_fq = e_lane >> 4, e_qw = q0 + wv * 32;
;       #pragma unroll
;       for (int qt = 0; qt < 2; ++qt) {
;         const float inv = FOX ? 1.0f / st1[qt] : 1.0f;
;         u16* yrow = Yp + (tok0 + e_qw + qt * 16 + e_fr) * ld + e_fq * 4;
;         #pragma unroll
;         for (int dt = 0; dt < 8; ++dt) {
;           uint2 g = *(const uint2*)(yrow + dt * 16);
;           uint2 pk;
;           pk.x = pack2(o[dt][qt][0] * inv * bf_lo(g.x), o[dt][qt][1] * inv * bf_hi(g.x));
;           pk.y = pack2(o[dt][qt][2] * inv * bf_lo(g.y), o[dt][qt][3] * inv * bf_hi(g.y));
;           *(uint2*)(yrow + dt * 16) = pk;
;         }
;       }
;     }
.LBB0_714:
	v_mbcnt_lo_u32_b32 v228, -1, 0
	v_mbcnt_hi_u32_b32 v228, -1, v228
	v_and_b32_e32 v228, 16, v228
	v_lshrrev_b32_e32 v229, 1, v228
	v_add_u32_e32 v228, v228, v229
	v_mov_b32_e32 v229, 0
	s_lshl_b32 s0, s40, 1
	s_barrier
	v_mbcnt_lo_u32_b32 v0, -1, 0
	v_mbcnt_hi_u32_b32 v0, -1, v0
	s_add_u32 s0, s3, s0
	v_and_or_b32 v36, v0, 15, s43
	v_lshrrev_b32_e32 v0, 1, v0
	s_addc_u32 s1, s36, 0
	v_and_b32_e32 v0, 24, v0
	v_lshl_add_u64 v[34:35], s[0:1], 0, v[0:1]
	v_mad_u64_u32 v[34:35], s[0:1], v36, s25, v[34:35]
	v_mad_i32_i24 v35, s39, v120, v35
	global_load_dwordx2 v[38:39], v[34:35], off
	global_load_dwordx2 v[40:41], v[34:35], off offset:32
	global_load_dwordx2 v[42:43], v[34:35], off offset:64
	global_load_dwordx2 v[44:45], v[34:35], off offset:96
	global_load_dwordx2 v[50:51], v[34:35], off offset:128
	global_load_dwordx2 v[52:53], v[34:35], off offset:160
	global_load_dwordx2 v[54:55], v[34:35], off offset:192
	global_load_dwordx2 v[56:57], v[34:35], off offset:224
	v_div_scale_f32 v0, s[0:1], v137, v137, 1.0
	v_rcp_f32_e32 v62, v0
	v_div_scale_f32 v63, vcc, 1.0, v137, 1.0
	v_fma_f32 v36, -v0, v62, 1.0
	v_fmac_f32_e32 v62, v36, v62
	v_mul_f32_e32 v64, v63, v62
	v_add_co_u32_e64 v36, s[0:1], s26, v34
	v_fma_f32 v65, -v0, v64, v63
	s_nop 0
	v_addc_co_u32_e64 v37, s[0:1], 0, v35, s[0:1]
	v_fmac_f32_e32 v64, v65, v62
	global_load_dwordx2 v[58:59], v[36:37], off
	global_load_dwordx2 v[60:61], v[36:37], off offset:32
	v_fma_f32 v0, -v0, v64, v63
	v_div_fmas_f32 v0, v0, v62, v64
	v_div_fixup_f32 v0, v0, v137, 1.0
	v_pk_mul_f32 v[62:63], v[94:95], v[0:1] op_sel_hi:[1,0]
	v_pk_mul_f32 v[64:65], v[96:97], v[0:1] op_sel_hi:[1,0]
	v_pk_mul_f32 v[66:67], v[90:91], v[0:1] op_sel_hi:[1,0]
	v_pk_mul_f32 v[68:69], v[92:93], v[0:1] op_sel_hi:[1,0]
	v_pk_mul_f32 v[86:87], v[86:87], v[0:1] op_sel_hi:[1,0]
	v_pk_mul_f32 v[88:89], v[88:89], v[0:1] op_sel_hi:[1,0]
	v_pk_mul_f32 v[82:83], v[82:83], v[0:1] op_sel_hi:[1,0]
	v_pk_mul_f32 v[84:85], v[84:85], v[0:1] op_sel_hi:[1,0]
	v_pk_mul_f32 v[78:79], v[78:79], v[0:1] op_sel_hi:[1,0]
	v_pk_mul_f32 v[46:47], v[46:47], v[0:1] op_sel_hi:[1,0]
	v_pk_mul_f32 v[48:49], v[48:49], v[0:1] op_sel_hi:[1,0]
	s_waitcnt vmcnt(9)
	v_lshlrev_b32_e32 v90, 16, v38
	v_and_b32_e32 v91, 0xffff0000, v38
	v_lshlrev_b32_e32 v38, 16, v39
	v_and_b32_e32 v39, 0xffff0000, v39
	s_waitcnt vmcnt(8)
	v_lshlrev_b32_e32 v92, 16, v40
	v_and_b32_e32 v93, 0xffff0000, v40
	v_lshlrev_b32_e32 v40, 16, v41
	v_and_b32_e32 v41, 0xffff0000, v41
	s_waitcnt vmcnt(7)
	v_lshlrev_b32_e32 v94, 16, v42
	v_and_b32_e32 v95, 0xffff0000, v42
	v_lshlrev_b32_e32 v42, 16, v43
	v_and_b32_e32 v43, 0xffff0000, v43
	s_waitcnt vmcnt(6)
	v_lshlrev_b32_e32 v96, 16, v44
	v_and_b32_e32 v97, 0xffff0000, v44
	v_lshlrev_b32_e32 v44, 16, v45
	v_and_b32_e32 v45, 0xffff0000, v45
	v_pk_mul_f32 v[62:63], v[62:63], v[90:91]
	v_pk_mul_f32 v[38:39], v[64:65], v[38:39]
	v_pk_mul_f32 v[64:65], v[66:67], v[92:93]
	v_pk_mul_f32 v[40:41], v[68:69], v[40:41]
	v_pk_mul_f32 v[66:67], v[86:87], v[94:95]
	v_pk_mul_f32 v[42:43], v[88:89], v[42:43]
	v_pk_mul_f32 v[68:69], v[82:83], v[96:97]
	v_pk_mul_f32 v[44:45], v[84:85], v[44:45]
	v_cvt_pk_bf16_f32 v62, v62, v63
	v_cvt_pk_bf16_f32 v63, v38, v39
	v_cvt_pk_bf16_f32 v38, v64, v65
	v_cvt_pk_bf16_f32 v39, v40, v41
	v_cvt_pk_bf16_f32 v40, v66, v67
	v_cvt_pk_bf16_f32 v41, v42, v43
	v_cvt_pk_bf16_f32 v42, v68, v69
	v_cvt_pk_bf16_f32 v43, v44, v45
	v_mov_b32_e32 v224, v62
	v_mov_b32_e32 v225, v63
	v_mov_b32_e32 v226, v38
	v_mov_b32_e32 v227, v39
	v_lshl_add_u64 v[230:231], v[34:35], 0, v[228:229]
	s_nop 0
	v_permlane16_swap_b32_e32 v224, v226
	v_permlane16_swap_b32_e32 v225, v227
	global_store_dwordx4 v[230:231], v[224:227], off
	s_nop 1
	v_mov_b32_e32 v224, v40
	v_mov_b32_e32 v225, v41
	v_mov_b32_e32 v226, v42
	v_mov_b32_e32 v227, v43
	v_lshl_add_u64 v[230:231], v[34:35], 0, v[228:229]
	s_nop 0
	v_permlane16_swap_b32_e32 v224, v226
	v_permlane16_swap_b32_e32 v225, v227
	global_store_dwordx4 v[230:231], v[224:227], off offset:64
	s_nop 1
	s_waitcnt vmcnt(7)
	v_lshlrev_b32_e32 v98, 16, v50
	v_and_b32_e32 v99, 0xffff0000, v50
	v_lshlrev_b32_e32 v40, 16, v51
	global_load_dwordx2 v[42:43], v[36:37], off offset:64
	v_and_b32_e32 v41, 0xffff0000, v51
	v_pk_mul_f32 v[44:45], v[80:81], v[0:1] op_sel_hi:[1,0]
	v_pk_mul_f32 v[78:79], v[78:79], v[98:99]
	v_pk_mul_f32 v[40:41], v[44:45], v[40:41]
	v_cvt_pk_bf16_f32 v38, v78, v79
	v_cvt_pk_bf16_f32 v39, v40, v41
	v_mov_b32_e32 v224, v38
	v_mov_b32_e32 v225, v39
	s_waitcnt vmcnt(7)
	v_lshlrev_b32_e32 v38, 16, v52
	v_and_b32_e32 v39, 0xffff0000, v52
	v_pk_mul_f32 v[40:41], v[74:75], v[0:1] op_sel_hi:[1,0]
	v_lshlrev_b32_e32 v44, 16, v53
	v_and_b32_e32 v45, 0xffff0000, v53
	v_pk_mul_f32 v[50:51], v[76:77], v[0:1] op_sel_hi:[1,0]
	v_pk_mul_f32 v[38:39], v[40:41], v[38:39]
	global_load_dwordx2 v[40:41], v[36:37], off offset:96
	v_pk_mul_f32 v[44:45], v[50:51], v[44:45]
	v_cvt_pk_bf16_f32 v38, v38, v39
	v_cvt_pk_bf16_f32 v39, v44, v45
	v_mov_b32_e32 v226, v38
	v_mov_b32_e32 v227, v39
	v_lshl_add_u64 v[230:231], v[34:35], 0, v[228:229]
	s_nop 0
	v_permlane16_swap_b32_e32 v224, v226
	v_permlane16_swap_b32_e32 v225, v227
	global_store_dwordx4 v[230:231], v[224:227], off offset:128
	s_nop 1
	s_waitcnt vmcnt(8)
	v_lshlrev_b32_e32 v38, 16, v54
	v_and_b32_e32 v39, 0xffff0000, v54
	v_pk_mul_f32 v[44:45], v[70:71], v[0:1] op_sel_hi:[1,0]
	v_lshlrev_b32_e32 v50, 16, v55
	v_and_b32_e32 v51, 0xffff0000, v55
	v_pk_mul_f32 v[52:53], v[72:73], v[0:1] op_sel_hi:[1,0]
	v_pk_mul_f32 v[38:39], v[44:45], v[38:39]
	v_pk_mul_f32 v[50:51], v[52:53], v[50:51]
	global_load_dwordx2 v[44:45], v[36:37], off offset:128
	v_cvt_pk_bf16_f32 v38, v38, v39
	v_cvt_pk_bf16_f32 v39, v50, v51
	v_mov_b32_e32 v224, v38
	v_mov_b32_e32 v225, v39
	s_waitcnt vmcnt(8)
; __device__ __forceinline__ float bf_lo(u32 v) { return __uint_as_float(v << 16); }
; __device__ __forceinline__ float bf_hi(u32 v) { return __uint_as_float(v & 0xffff0000u); }
; template <bool FOX>
; __device__ __forceinline__ void attn_pair(const Params& p, int it, char* smem, const int wv) {
;     ...
;     {
;       const int tid3 = opaque_tid(wv);
;       const int e_lane = tid3 & 63, e_fr = e_lane & 15, e_fq = e_lane >> 4, e_qw = q0 + wv * 32;
;       #pragma unroll
;       for (int qt = 0; qt < 2; ++qt) {
;         const float inv = FOX ? 1.0f / st1[qt] : 1.0f;
;         u16* yrow = Yp + (tok0 + e_qw + qt * 16 + e_fr) * ld + e_fq * 4;
;         #pragma unroll
;         for (int dt = 0; dt < 8; ++dt) {
;           uint2 g = *(const uint2*)(yrow + dt * 16);
;           uint2 pk;
;           pk.x = pack2(o[dt][qt][0] * inv * bf_lo(g.x), o[dt][qt][1] * inv * bf_hi(g.x));
;           pk.y = pack2(o[dt][qt][2] * inv * bf_lo(g.y), o[dt][qt][3] * inv * bf_hi(g.y));
;           *(uint2*)(yrow + dt * 16) = pk;
;         }
;       }
;     }
	v_lshlrev_b32_e32 v38, 16, v56
	v_and_b32_e32 v39, 0xffff0000, v56
	v_pk_mul_f32 v[38:39], v[46:47], v[38:39]
	v_lshlrev_b32_e32 v46, 16, v57
	v_and_b32_e32 v47, 0xffff0000, v57
	v_div_scale_f32 v0, s[0:1], v130, v130, 1.0
	v_pk_mul_f32 v[46:47], v[48:49], v[46:47]
	v_rcp_f32_e32 v48, v0
	global_load_dwordx2 v[50:51], v[36:37], off offset:160
	v_cvt_pk_bf16_f32 v38, v38, v39
	v_cvt_pk_bf16_f32 v39, v46, v47
	v_mov_b32_e32 v226, v38
	v_mov_b32_e32 v227, v39
	v_lshl_add_u64 v[230:231], v[34:35], 0, v[228:229]
	s_nop 0
	v_permlane16_swap_b32_e32 v224, v226
	v_permlane16_swap_b32_e32 v225, v227
	global_store_dwordx4 v[230:231], v[224:227], off offset:192
	s_nop 1
	v_fma_f32 v34, -v0, v48, 1.0
	global_load_dwordx2 v[46:47], v[36:37], off offset:192
	v_fmac_f32_e32 v48, v34, v48
	v_div_scale_f32 v34, vcc, 1.0, v130, 1.0
	v_mul_f32_e32 v38, v34, v48
	v_fma_f32 v35, -v0, v38, v34
	v_fmac_f32_e32 v38, v35, v48
	v_fma_f32 v0, -v0, v38, v34
	global_load_dwordx2 v[34:35], v[36:37], off offset:224
	v_div_fmas_f32 v0, v0, v48, v38
	v_div_fixup_f32 v0, v0, v130, 1.0
	s_waitcnt vmcnt(11)
	v_lshlrev_b32_e32 v38, 16, v58
	v_and_b32_e32 v39, 0xffff0000, v58
	v_pk_mul_f32 v[30:31], v[30:31], v[0:1] op_sel_hi:[1,0]
	v_pk_mul_f32 v[32:33], v[32:33], v[0:1] op_sel_hi:[1,0]
	v_pk_mul_f32 v[30:31], v[30:31], v[38:39]
	v_lshlrev_b32_e32 v38, 16, v59
	v_and_b32_e32 v39, 0xffff0000, v59
	v_pk_mul_f32 v[32:33], v[32:33], v[38:39]
	v_cvt_pk_bf16_f32 v30, v30, v31
	v_cvt_pk_bf16_f32 v31, v32, v33
	v_mov_b32_e32 v224, v30
	v_mov_b32_e32 v225, v31
	s_waitcnt vmcnt(10)
	v_lshlrev_b32_e32 v30, 16, v60
	v_and_b32_e32 v31, 0xffff0000, v60
	v_pk_mul_f32 v[26:27], v[26:27], v[0:1] op_sel_hi:[1,0]
	v_pk_mul_f32 v[28:29], v[28:29], v[0:1] op_sel_hi:[1,0]
	v_pk_mul_f32 v[26:27], v[26:27], v[30:31]
	v_lshlrev_b32_e32 v30, 16, v61
	v_and_b32_e32 v31, 0xffff0000, v61
	v_pk_mul_f32 v[28:29], v[28:29], v[30:31]
	v_cvt_pk_bf16_f32 v26, v26, v27
	v_cvt_pk_bf16_f32 v27, v28, v29
	v_mov_b32_e32 v226, v26
	v_mov_b32_e32 v227, v27
	v_lshl_add_u64 v[230:231], v[36:37], 0, v[228:229]
	s_nop 0
	v_permlane16_swap_b32_e32 v224, v226
	v_permlane16_swap_b32_e32 v225, v227
	global_store_dwordx4 v[230:231], v[224:227], off
	s_nop 1
	v_pk_mul_f32 v[22:23], v[22:23], v[0:1] op_sel_hi:[1,0]
	s_waitcnt vmcnt(8)
	v_lshlrev_b32_e32 v26, 16, v42
	v_and_b32_e32 v27, 0xffff0000, v42
	v_pk_mul_f32 v[22:23], v[22:23], v[26:27]
	v_lshlrev_b32_e32 v26, 16, v43
	v_and_b32_e32 v27, 0xffff0000, v43
	v_pk_mul_f32 v[24:25], v[24:25], v[0:1] op_sel_hi:[1,0]
	v_cvt_pk_bf16_f32 v22, v22, v23
	v_pk_mul_f32 v[24:25], v[24:25], v[26:27]
	v_pk_mul_f32 v[18:19], v[18:19], v[0:1] op_sel_hi:[1,0]
	v_cvt_pk_bf16_f32 v23, v24, v25
	v_mov_b32_e32 v224, v22
	v_mov_b32_e32 v225, v23
	v_pk_mul_f32 v[20:21], v[20:21], v[0:1] op_sel_hi:[1,0]
	v_pk_mul_f32 v[14:15], v[14:15], v[0:1] op_sel_hi:[1,0]
	v_pk_mul_f32 v[16:17], v[16:17], v[0:1] op_sel_hi:[1,0]
	v_pk_mul_f32 v[10:11], v[10:11], v[0:1] op_sel_hi:[1,0]
	s_waitcnt vmcnt(7)
	v_lshlrev_b32_e32 v22, 16, v40
	v_and_b32_e32 v23, 0xffff0000, v40
	v_pk_mul_f32 v[18:19], v[18:19], v[22:23]
	v_lshlrev_b32_e32 v22, 16, v41
	v_and_b32_e32 v23, 0xffff0000, v41
	v_pk_mul_f32 v[20:21], v[20:21], v[22:23]
	v_cvt_pk_bf16_f32 v18, v18, v19
	v_cvt_pk_bf16_f32 v19, v20, v21
	v_mov_b32_e32 v226, v18
	v_mov_b32_e32 v227, v19
	v_lshl_add_u64 v[230:231], v[36:37], 0, v[228:229]
	s_nop 0
	v_permlane16_swap_b32_e32 v224, v226
	v_permlane16_swap_b32_e32 v225, v227
	global_store_dwordx4 v[230:231], v[224:227], off offset:64
	s_nop 1
	v_pk_mul_f32 v[12:13], v[12:13], v[0:1] op_sel_hi:[1,0]
	v_pk_mul_f32 v[6:7], v[6:7], v[0:1] op_sel_hi:[1,0]
	v_pk_mul_f32 v[8:9], v[8:9], v[0:1] op_sel_hi:[1,0]
	v_pk_mul_f32 v[2:3], v[2:3], v[0:1] op_sel_hi:[1,0]
	s_waitcnt vmcnt(6)
	v_lshlrev_b32_e32 v18, 16, v44
	v_and_b32_e32 v19, 0xffff0000, v44
	v_pk_mul_f32 v[14:15], v[14:15], v[18:19]
	v_lshlrev_b32_e32 v18, 16, v45
	v_and_b32_e32 v19, 0xffff0000, v45
	v_pk_mul_f32 v[16:17], v[16:17], v[18:19]
	v_cvt_pk_bf16_f32 v14, v14, v15
	v_cvt_pk_bf16_f32 v15, v16, v17
	v_mov_b32_e32 v224, v14
	v_mov_b32_e32 v225, v15
	v_pk_mul_f32 v[4:5], v[4:5], v[0:1] op_sel_hi:[1,0]
	s_mov_b64 s[0:1], 0
	s_waitcnt vmcnt(5)
	v_lshlrev_b32_e32 v14, 16, v50
	v_and_b32_e32 v15, 0xffff0000, v50
	v_pk_mul_f32 v[10:11], v[10:11], v[14:15]
	v_lshlrev_b32_e32 v14, 16, v51
	v_and_b32_e32 v15, 0xffff0000, v51
	v_pk_mul_f32 v[12:13], v[12:13], v[14:15]
	v_cvt_pk_bf16_f32 v10, v10, v11
	v_cvt_pk_bf16_f32 v11, v12, v13
	v_mov_b32_e32 v226, v10
	v_mov_b32_e32 v227, v11
	v_lshl_add_u64 v[230:231], v[36:37], 0, v[228:229]
	s_nop 0
	v_permlane16_swap_b32_e32 v224, v226
	v_permlane16_swap_b32_e32 v225, v227
	global_store_dwordx4 v[230:231], v[224:227], off offset:128
	s_nop 1
	s_waitcnt vmcnt(4)
	v_lshlrev_b32_e32 v10, 16, v46
	v_and_b32_e32 v11, 0xffff0000, v46
	v_pk_mul_f32 v[6:7], v[6:7], v[10:11]
	v_lshlrev_b32_e32 v10, 16, v47
	v_and_b32_e32 v11, 0xffff0000, v47
	v_pk_mul_f32 v[8:9], v[8:9], v[10:11]
	v_cvt_pk_bf16_f32 v6, v6, v7
	v_cvt_pk_bf16_f32 v7, v8, v9
	v_mov_b32_e32 v224, v6
	v_mov_b32_e32 v225, v7
	s_waitcnt vmcnt(3)
	v_lshlrev_b32_e32 v6, 16, v34
	v_and_b32_e32 v7, 0xffff0000, v34
	v_pk_mul_f32 v[2:3], v[2:3], v[6:7]
	v_lshlrev_b32_e32 v6, 16, v35
	v_and_b32_e32 v7, 0xffff0000, v35
	v_pk_mul_f32 v[4:5], v[4:5], v[6:7]
	v_cvt_pk_bf16_f32 v2, v2, v3
	v_cvt_pk_bf16_f32 v3, v4, v5
	v_mov_b32_e32 v226, v2
	v_mov_b32_e32 v227, v3
	v_lshl_add_u64 v[230:231], v[36:37], 0, v[228:229]
	s_nop 0
	v_permlane16_swap_b32_e32 v224, v226
	v_permlane16_swap_b32_e32 v225, v227
	global_store_dwordx4 v[230:231], v[224:227], off offset:192
	s_nop 1
